# P5 attention loops: LDS fragment reads de-serialized (own registers, counted lgkmcnt) and mask-free softmax path for unmasked tiles
# speedup vs baseline: 1.0489x; 1.0041x over previous
.LBB0_628:
	s_and_b32 s51, s33, 1
	s_add_i32 s0, s29, 0xfffffbf1
	s_cmp_gt_u32 s0, s26
	s_cbranch_scc1 .LBB0_642
	s_mul_i32 s0, s51, 0x4400
	v_add_u32_e32 v178, s0, v174
	ds_read_b128 v[212:215], v178
	ds_read_b128 v[216:219], v178 offset:32
	ds_read_b128 v[220:223], v178 offset:64
	ds_read_b128 v[224:227], v178 offset:96
	ds_read_b128 v[228:231], v178 offset:128
	ds_read_b128 v[236:239], v178 offset:160
	ds_read_b128 v[240:243], v178 offset:192
	ds_read_b128 v[244:247], v178 offset:224
	s_cmp_le_u32 s29, s26
	s_cselect_b64 s[6:7], -1, 0
	s_cmpk_gt_i32 s27, 0x9d
	s_cselect_b64 s[0:1], -1, 0
	s_and_b64 s[0:1], s[6:7], s[0:1]
	s_mov_b64 s[2:3], -1
	s_waitcnt lgkmcnt(7)
	v_mfma_f32_32x32x16_bf16 v[66:81], v[212:215], v[82:85], 0
	s_waitcnt lgkmcnt(6)
	v_mfma_f32_32x32x16_bf16 v[66:81], v[216:219], v[86:89], v[66:81]
	s_waitcnt lgkmcnt(5)
	v_mfma_f32_32x32x16_bf16 v[66:81], v[220:223], v[90:93], v[66:81]
	s_waitcnt lgkmcnt(4)
	v_mfma_f32_32x32x16_bf16 v[66:81], v[224:227], v[94:97], v[66:81]
	s_waitcnt lgkmcnt(3)
	v_mfma_f32_32x32x16_bf16 v[66:81], v[228:231], v[98:101], v[66:81]
	s_waitcnt lgkmcnt(2)
	v_mfma_f32_32x32x16_bf16 v[66:81], v[236:239], v[102:105], v[66:81]
	s_waitcnt lgkmcnt(1)
	v_mfma_f32_32x32x16_bf16 v[66:81], v[240:243], v[106:109], v[66:81]
	s_waitcnt lgkmcnt(0)
	v_mfma_f32_32x32x16_bf16 v[66:81], v[244:247], v[110:113], v[66:81]
	s_and_b64 vcc, exec, s[0:1]
	v_add_u32_e32 v141, s27, v175
	s_cbranch_vccnz .LBB0_631
	v_add_u32_e32 v143, 0x3f0, v141
	v_max_i32_e32 v144, 31, v143
	v_subrev_u32_e32 v144, 31, v144
	v_cmp_lt_i32_e32 vcc, 30, v143
	v_add_u32_e32 v143, 0x3e0, v141
	v_min_u32_e32 v144, 0x1ff, v144
	s_add_i32 s2, 0, 0x12000
	v_max_i32_e32 v145, 31, v143
	v_lshl_add_u32 v144, v144, 2, s2
	v_subrev_u32_e32 v145, 31, v145
	v_add_u32_e32 v146, 0x3d0, v141
	ds_read_b32 v144, v144
	v_min_u32_e32 v145, 0x1ff, v145
	v_max_i32_e32 v147, 31, v146
	v_lshl_add_u32 v145, v145, 2, s2
	v_subrev_u32_e32 v147, 31, v147
	ds_read_b32 v145, v145
	v_min_u32_e32 v147, 0x1ff, v147
	v_lshl_add_u32 v147, v147, 2, s2
	ds_read_b32 v147, v147
	s_waitcnt lgkmcnt(2)
	v_add_f32_e32 v144, v66, v144
	s_or_b64 vcc, s[6:7], vcc
	v_cndmask_b32_e32 v144, v162, v144, vcc
	v_cmp_lt_i32_e32 vcc, 30, v143
	s_waitcnt lgkmcnt(1)
	v_add_f32_e32 v145, v67, v145
	s_or_b64 vcc, s[6:7], vcc
	v_cndmask_b32_e32 v145, v162, v145, vcc
	v_cmp_lt_i32_e32 vcc, 30, v146
	s_waitcnt lgkmcnt(0)
	v_add_f32_e32 v147, v68, v147
	s_or_b64 vcc, s[6:7], vcc
	v_cndmask_b32_e32 v146, v162, v147, vcc
	v_add_u32_e32 v147, 0x3c0, v141
	v_max_i32_e32 v148, 31, v147
	v_subrev_u32_e32 v148, 31, v148
	v_min_u32_e32 v148, 0x1ff, v148
	v_lshl_add_u32 v148, v148, 2, s2
	ds_read_b32 v148, v148
	v_cmp_lt_i32_e32 vcc, 30, v147
	s_or_b64 vcc, s[6:7], vcc
	v_max3_f32 v143, v144, s47, v145
	s_waitcnt lgkmcnt(0)
	v_add_f32_e32 v148, v69, v148
	v_cndmask_b32_e32 v147, v162, v148, vcc
	v_add_u32_e32 v148, 0x3b0, v141
	v_max_i32_e32 v149, 31, v148
	v_subrev_u32_e32 v149, 31, v149
	v_min_u32_e32 v149, 0x1ff, v149
	v_lshl_add_u32 v149, v149, 2, s2
	ds_read_b32 v149, v149
	v_cmp_lt_i32_e32 vcc, 30, v148
	s_or_b64 vcc, s[6:7], vcc
	v_max3_f32 v143, v143, v146, v147
	s_waitcnt lgkmcnt(0)
	v_add_f32_e32 v149, v70, v149
	v_cndmask_b32_e32 v148, v162, v149, vcc
	v_add_u32_e32 v149, 0x3a0, v141
	v_max_i32_e32 v150, 31, v149
	v_subrev_u32_e32 v150, 31, v150
	v_min_u32_e32 v150, 0x1ff, v150
	v_lshl_add_u32 v150, v150, 2, s2
	ds_read_b32 v150, v150
	v_cmp_lt_i32_e32 vcc, 30, v149
	s_or_b64 vcc, s[6:7], vcc
	s_waitcnt lgkmcnt(0)
	v_add_f32_e32 v150, v71, v150
	v_cndmask_b32_e32 v149, v162, v150, vcc
	v_add_u32_e32 v150, 0x390, v141
	v_max_i32_e32 v151, 31, v150
	v_subrev_u32_e32 v151, 31, v151
	v_min_u32_e32 v151, 0x1ff, v151
	v_lshl_add_u32 v151, v151, 2, s2
	ds_read_b32 v151, v151
	v_cmp_lt_i32_e32 vcc, 30, v150
	s_or_b64 vcc, s[6:7], vcc
	v_max3_f32 v143, v143, v148, v149
	s_waitcnt lgkmcnt(0)
	v_add_f32_e32 v151, v72, v151
	v_cndmask_b32_e32 v150, v162, v151, vcc
	v_add_u32_e32 v151, 0x380, v141
	v_max_i32_e32 v152, 31, v151
	v_subrev_u32_e32 v152, 31, v152
	v_min_u32_e32 v152, 0x1ff, v152
	v_lshl_add_u32 v152, v152, 2, s2
	ds_read_b32 v152, v152
	v_cmp_lt_i32_e32 vcc, 30, v151
	s_or_b64 vcc, s[6:7], vcc
	s_waitcnt lgkmcnt(0)
	v_add_f32_e32 v152, v73, v152
	v_cndmask_b32_e32 v151, v162, v152, vcc
	v_add_u32_e32 v152, 0x2f0, v141
	v_max_i32_e32 v153, 31, v152
	v_subrev_u32_e32 v153, 31, v153
	v_min_u32_e32 v153, 0x1ff, v153
	v_lshl_add_u32 v153, v153, 2, s2
	ds_read_b32 v153, v153
	v_cmp_lt_i32_e32 vcc, 30, v152
	s_or_b64 vcc, s[6:7], vcc
	v_max3_f32 v143, v143, v150, v151
	s_waitcnt lgkmcnt(0)
	v_add_f32_e32 v153, v74, v153
	v_cndmask_b32_e32 v152, v162, v153, vcc
	v_add_u32_e32 v153, 0x2e0, v141
	v_max_i32_e32 v154, 31, v153
	v_subrev_u32_e32 v154, 31, v154
	v_min_u32_e32 v154, 0x1ff, v154
	v_lshl_add_u32 v154, v154, 2, s2
	ds_read_b32 v154, v154
	v_cmp_lt_i32_e32 vcc, 30, v153
	s_or_b64 vcc, s[6:7], vcc
	s_waitcnt lgkmcnt(0)
	v_add_f32_e32 v154, v75, v154
	v_cndmask_b32_e32 v153, v162, v154, vcc
	v_add_u32_e32 v154, 0x2d0, v141
	v_max_i32_e32 v155, 31, v154
	v_subrev_u32_e32 v155, 31, v155
	v_min_u32_e32 v155, 0x1ff, v155
	v_lshl_add_u32 v155, v155, 2, s2
	ds_read_b32 v155, v155
	v_cmp_lt_i32_e32 vcc, 30, v154
	s_or_b64 vcc, s[6:7], vcc
	v_max3_f32 v143, v143, v152, v153
	s_waitcnt lgkmcnt(0)
	v_add_f32_e32 v155, v76, v155
	v_cndmask_b32_e32 v154, v162, v155, vcc
	v_add_u32_e32 v155, 0x2c0, v141
	v_max_i32_e32 v156, 31, v155
	v_subrev_u32_e32 v156, 31, v156
	v_min_u32_e32 v156, 0x1ff, v156
	v_lshl_add_u32 v156, v156, 2, s2
	ds_read_b32 v156, v156
	v_cmp_lt_i32_e32 vcc, 30, v155
	s_or_b64 vcc, s[6:7], vcc
	s_waitcnt lgkmcnt(0)
	v_add_f32_e32 v156, v77, v156
	v_cndmask_b32_e32 v155, v162, v156, vcc
	v_add_u32_e32 v156, 0x2b0, v141
	v_max_i32_e32 v157, 31, v156
	v_subrev_u32_e32 v157, 31, v157
	v_min_u32_e32 v157, 0x1ff, v157
	v_lshl_add_u32 v157, v157, 2, s2
	ds_read_b32 v157, v157
	v_cmp_lt_i32_e32 vcc, 30, v156
	s_or_b64 vcc, s[6:7], vcc
	v_max3_f32 v143, v143, v154, v155
	s_waitcnt lgkmcnt(0)
	v_add_f32_e32 v157, v78, v157
	v_cndmask_b32_e32 v156, v162, v157, vcc
	v_add_u32_e32 v157, 0x2a0, v141
	v_max_i32_e32 v158, 31, v157
	v_subrev_u32_e32 v158, 31, v158
	v_min_u32_e32 v158, 0x1ff, v158
	v_lshl_add_u32 v158, v158, 2, s2
	ds_read_b32 v158, v158
	v_cmp_lt_i32_e32 vcc, 30, v157
	s_or_b64 vcc, s[6:7], vcc
	s_waitcnt lgkmcnt(0)
	v_add_f32_e32 v158, v79, v158
	v_cndmask_b32_e32 v157, v162, v158, vcc
	v_add_u32_e32 v158, 0x290, v141
	v_max_i32_e32 v159, 31, v158
	v_subrev_u32_e32 v159, 31, v159
	v_min_u32_e32 v159, 0x1ff, v159
	v_lshl_add_u32 v159, v159, 2, s2
	ds_read_b32 v159, v159
	v_cmp_lt_i32_e32 vcc, 30, v158
	s_or_b64 vcc, s[6:7], vcc
	v_max3_f32 v143, v143, v156, v157
	s_waitcnt lgkmcnt(0)
	v_add_f32_e32 v159, v80, v159
	v_cndmask_b32_e32 v158, v162, v159, vcc
	v_add_u32_e32 v159, 0x280, v141
	v_max_i32_e32 v179, 31, v159
	v_subrev_u32_e32 v179, 31, v179
	v_min_u32_e32 v179, 0x1ff, v179
	v_lshl_add_u32 v179, v179, 2, s2
	ds_read_b32 v179, v179
	v_cmp_lt_i32_e32 vcc, 30, v159
	s_or_b64 vcc, s[6:7], vcc
	s_mov_b64 s[2:3], 0
	s_waitcnt lgkmcnt(0)
	v_add_f32_e32 v179, v81, v179
	v_cndmask_b32_e32 v159, v162, v179, vcc
	v_max3_f32 v143, v143, v158, v159

.LBB0_635:
	s_cmp_lg_u32 s6, 0
	s_cbranch_scc1 .Llean635
	v_sub_f32_e32 v66, v144, v176
	v_exp_f32_e32 v66, v66
	v_sub_f32_e32 v67, v145, v176
	v_cmp_lt_f32_e32 vcc, s49, v144
	v_exp_f32_e32 v67, v67
	s_or_b64 vcc, s[6:7], vcc
	v_cndmask_b32_e32 v179, 0, v66, vcc
	v_cmp_lt_f32_e32 vcc, s49, v145
	v_sub_f32_e32 v66, v146, v176
	s_or_b64 vcc, s[6:7], vcc
	v_exp_f32_e32 v66, v66
	v_cndmask_b32_e32 v180, 0, v67, vcc
	v_sub_f32_e32 v67, v147, v176
	v_cmp_lt_f32_e32 vcc, s49, v146
	v_exp_f32_e32 v67, v67
	s_or_b64 vcc, s[6:7], vcc
	v_cndmask_b32_e32 v181, 0, v66, vcc
	v_cmp_lt_f32_e32 vcc, s49, v147
	v_sub_f32_e32 v66, v148, v176
	s_or_b64 vcc, s[6:7], vcc
	v_exp_f32_e32 v66, v66
	v_cndmask_b32_e32 v183, 0, v67, vcc
	v_sub_f32_e32 v67, v149, v176
	v_cmp_lt_f32_e32 vcc, s49, v148
	v_exp_f32_e32 v67, v67
	s_or_b64 vcc, s[6:7], vcc
	v_cndmask_b32_e32 v184, 0, v66, vcc
	v_cmp_lt_f32_e32 vcc, s49, v149
	v_sub_f32_e32 v66, v150, v176
	s_or_b64 vcc, s[6:7], vcc
	v_exp_f32_e32 v66, v66
	v_cndmask_b32_e32 v185, 0, v67, vcc
	v_sub_f32_e32 v67, v151, v176
	v_cmp_lt_f32_e32 vcc, s49, v150
	v_exp_f32_e32 v67, v67
	s_or_b64 vcc, s[6:7], vcc
	v_cndmask_b32_e32 v186, 0, v66, vcc
	v_cmp_lt_f32_e32 vcc, s49, v151
	v_sub_f32_e32 v66, v152, v176
	s_or_b64 vcc, s[6:7], vcc
	v_exp_f32_e32 v66, v66
	v_cndmask_b32_e32 v187, 0, v67, vcc
	v_sub_f32_e32 v67, v153, v176
	v_cmp_lt_f32_e32 vcc, s49, v152
	v_exp_f32_e32 v67, v67
	s_or_b64 vcc, s[6:7], vcc
	v_cndmask_b32_e32 v188, 0, v66, vcc
	v_cmp_lt_f32_e32 vcc, s49, v153
	v_sub_f32_e32 v66, v154, v176
	s_or_b64 vcc, s[6:7], vcc
	v_exp_f32_e32 v66, v66
	v_cndmask_b32_e32 v189, 0, v67, vcc
	v_sub_f32_e32 v67, v155, v176
	v_cmp_lt_f32_e32 vcc, s49, v154
	v_exp_f32_e32 v67, v67
	s_or_b64 vcc, s[6:7], vcc
	v_cndmask_b32_e32 v190, 0, v66, vcc
	v_cmp_lt_f32_e32 vcc, s49, v155
	v_sub_f32_e32 v66, v156, v176
	s_or_b64 vcc, s[6:7], vcc
	v_exp_f32_e32 v66, v66
	v_cndmask_b32_e32 v191, 0, v67, vcc
	v_sub_f32_e32 v67, v157, v176
	v_cmp_lt_f32_e32 vcc, s49, v156
	v_exp_f32_e32 v67, v67
	s_or_b64 vcc, s[6:7], vcc
	v_cndmask_b32_e32 v192, 0, v66, vcc
	v_cmp_lt_f32_e32 vcc, s49, v157
	v_sub_f32_e32 v66, v158, v176
	s_or_b64 vcc, s[6:7], vcc
	v_exp_f32_e32 v66, v66
	v_cndmask_b32_e32 v193, 0, v67, vcc
	v_sub_f32_e32 v67, v159, v176
	v_cmp_lt_f32_e32 vcc, s49, v158
	v_exp_f32_e32 v67, v67
	s_or_b64 vcc, s[6:7], vcc
	v_cndmask_b32_e32 v194, 0, v66, vcc
	v_cmp_lt_f32_e32 vcc, s49, v159
	s_or_b64 vcc, s[6:7], vcc
	s_xor_b64 s[0:1], s[0:1], -1
	v_cndmask_b32_e32 v195, 0, v67, vcc
	s_branch .Ljoin635
.Llean635:
	v_sub_f32_e32 v66, v144, v176
	v_exp_f32_e32 v66, v66
	v_sub_f32_e32 v67, v145, v176
	v_exp_f32_e32 v67, v67
	v_mov_b32_e32 v179, v66
	v_sub_f32_e32 v66, v146, v176
	v_exp_f32_e32 v66, v66
	v_mov_b32_e32 v180, v67
	v_sub_f32_e32 v67, v147, v176
	v_exp_f32_e32 v67, v67
	v_mov_b32_e32 v181, v66
	v_sub_f32_e32 v66, v148, v176
	v_exp_f32_e32 v66, v66
	v_mov_b32_e32 v183, v67
	v_sub_f32_e32 v67, v149, v176
	v_exp_f32_e32 v67, v67
	v_mov_b32_e32 v184, v66
	v_sub_f32_e32 v66, v150, v176
	v_exp_f32_e32 v66, v66
	v_mov_b32_e32 v185, v67
	v_sub_f32_e32 v67, v151, v176
	v_exp_f32_e32 v67, v67
	v_mov_b32_e32 v186, v66
	v_sub_f32_e32 v66, v152, v176
	v_exp_f32_e32 v66, v66
	v_mov_b32_e32 v187, v67
	v_sub_f32_e32 v67, v153, v176
	v_exp_f32_e32 v67, v67
	v_mov_b32_e32 v188, v66
	v_sub_f32_e32 v66, v154, v176
	v_exp_f32_e32 v66, v66
	v_mov_b32_e32 v189, v67
	v_sub_f32_e32 v67, v155, v176
	v_exp_f32_e32 v67, v67
	v_mov_b32_e32 v190, v66
	v_sub_f32_e32 v66, v156, v176
	v_exp_f32_e32 v66, v66
	v_mov_b32_e32 v191, v67
	v_sub_f32_e32 v67, v157, v176
	v_exp_f32_e32 v67, v67
	v_mov_b32_e32 v192, v66
	v_sub_f32_e32 v66, v158, v176
	v_exp_f32_e32 v66, v66
	v_mov_b32_e32 v193, v67
	v_sub_f32_e32 v67, v159, v176
	v_exp_f32_e32 v67, v67
	v_mov_b32_e32 v194, v66
	s_xor_b64 s[0:1], s[0:1], -1
	v_mov_b32_e32 v195, v67
.Ljoin635:
	v_cvt_pk_bf16_f32 v66, v179, v180
	v_cvt_pk_bf16_f32 v67, v181, v183
	v_cvt_pk_bf16_f32 v68, v184, v185
	v_cvt_pk_bf16_f32 v69, v186, v187
	v_cvt_pk_bf16_f32 v70, v188, v189
	v_cvt_pk_bf16_f32 v71, v190, v191
	v_cvt_pk_bf16_f32 v72, v192, v193
	v_cvt_pk_bf16_f32 v73, v194, v195
	s_mul_i32 s2, s51, 0x4800
	v_add_u32_e32 v143, s2, v173
	ds_read_b128 v[212:215], v143 offset:34816
	ds_read_b128 v[216:219], v143 offset:34848
	ds_read_b128 v[220:223], v143 offset:39424
	ds_read_b128 v[224:227], v143 offset:39456
	ds_read_b128 v[228:231], v143 offset:44032
	ds_read_b128 v[236:239], v143 offset:44064
	ds_read_b128 v[240:243], v143 offset:48640
	ds_read_b128 v[244:247], v143 offset:48672
	s_waitcnt lgkmcnt(7)
	v_mfma_f32_32x32x16_bf16 v[50:65], v[212:215], v[66:69], v[50:65]
	s_waitcnt lgkmcnt(6)
	v_mfma_f32_32x32x16_bf16 v[50:65], v[216:219], v[70:73], v[50:65]
	s_waitcnt lgkmcnt(5)
	v_mfma_f32_32x32x16_bf16 v[34:49], v[220:223], v[66:69], v[34:49]
	s_waitcnt lgkmcnt(4)
	v_mfma_f32_32x32x16_bf16 v[34:49], v[224:227], v[70:73], v[34:49]
	s_waitcnt lgkmcnt(3)
	v_mfma_f32_32x32x16_bf16 v[18:33], v[228:231], v[66:69], v[18:33]
	s_waitcnt lgkmcnt(2)
	v_mfma_f32_32x32x16_bf16 v[18:33], v[236:239], v[70:73], v[18:33]
	s_waitcnt lgkmcnt(1)
	v_mfma_f32_32x32x16_bf16 v[2:17], v[240:243], v[66:69], v[2:17]
	s_waitcnt lgkmcnt(0)
	v_mfma_f32_32x32x16_bf16 v[2:17], v[244:247], v[70:73], v[2:17]
	ds_read_b128 v[212:215], v178 offset:8704
	ds_read_b128 v[216:219], v178 offset:8736
	ds_read_b128 v[220:223], v178 offset:8768
	ds_read_b128 v[224:227], v178 offset:8800
	ds_read_b128 v[228:231], v178 offset:8832
	ds_read_b128 v[236:239], v178 offset:8864
	ds_read_b128 v[240:243], v178 offset:8896
	ds_read_b128 v[244:247], v178 offset:8928
	s_waitcnt lgkmcnt(7)
	v_mfma_f32_32x32x16_bf16 v[66:81], v[212:215], v[82:85], 0
	s_waitcnt lgkmcnt(6)
	v_mfma_f32_32x32x16_bf16 v[66:81], v[216:219], v[86:89], v[66:81]
	s_waitcnt lgkmcnt(5)
	v_mfma_f32_32x32x16_bf16 v[66:81], v[220:223], v[90:93], v[66:81]
	s_waitcnt lgkmcnt(4)
	v_mfma_f32_32x32x16_bf16 v[66:81], v[224:227], v[94:97], v[66:81]
	s_waitcnt lgkmcnt(3)
	v_mfma_f32_32x32x16_bf16 v[66:81], v[228:231], v[98:101], v[66:81]
	s_waitcnt lgkmcnt(2)
	v_mfma_f32_32x32x16_bf16 v[66:81], v[236:239], v[102:105], v[66:81]
	s_waitcnt lgkmcnt(1)
	v_mfma_f32_32x32x16_bf16 v[66:81], v[240:243], v[106:109], v[66:81]
	s_waitcnt lgkmcnt(0)
	v_mfma_f32_32x32x16_bf16 v[66:81], v[244:247], v[110:113], v[66:81]
	s_andn2_b64 vcc, exec, s[0:1]
	s_mov_b64 s[0:1], -1
	s_cbranch_vccnz .LBB0_637
	v_add_u32_e32 v144, 0x1f0, v141
	v_max_i32_e32 v145, 31, v144
	v_subrev_u32_e32 v145, 31, v145
	v_min_u32_e32 v145, 0x1ff, v145
	s_add_i32 s0, 0, 0x12000
	v_lshl_add_u32 v145, v145, 2, s0
	ds_read_b32 v145, v145
	v_cmp_lt_i32_e32 vcc, 30, v144
	s_or_b64 vcc, s[6:7], vcc
	s_waitcnt lgkmcnt(0)
	v_add_f32_e32 v145, v66, v145
	v_cndmask_b32_e32 v144, v162, v145, vcc
	v_add_u32_e32 v145, 0x1e0, v141
	v_max_i32_e32 v146, 31, v145
	v_subrev_u32_e32 v146, 31, v146
	v_min_u32_e32 v146, 0x1ff, v146
	v_lshl_add_u32 v146, v146, 2, s0
	ds_read_b32 v146, v146
	v_cmp_lt_i32_e32 vcc, 30, v145
	s_or_b64 vcc, s[6:7], vcc
	s_waitcnt lgkmcnt(0)
	v_add_f32_e32 v146, v67, v146
	v_cndmask_b32_e32 v145, v162, v146, vcc
	v_add_u32_e32 v146, 0x1d0, v141
	v_max_i32_e32 v147, 31, v146
	v_subrev_u32_e32 v147, 31, v147
	v_min_u32_e32 v147, 0x1ff, v147
	v_lshl_add_u32 v147, v147, 2, s0
	ds_read_b32 v147, v147
	v_cmp_lt_i32_e32 vcc, 30, v146
	s_or_b64 vcc, s[6:7], vcc
	v_max3_f32 v148, v144, s47, v145
	s_waitcnt lgkmcnt(0)
	v_add_f32_e32 v147, v68, v147
	v_cndmask_b32_e32 v146, v162, v147, vcc
	v_add_u32_e32 v147, 0x1c0, v141
	v_max_i32_e32 v149, 31, v147
	v_subrev_u32_e32 v149, 31, v149
	v_min_u32_e32 v149, 0x1ff, v149
	v_lshl_add_u32 v149, v149, 2, s0
	ds_read_b32 v149, v149
	v_cmp_lt_i32_e32 vcc, 30, v147
	s_or_b64 vcc, s[6:7], vcc
	s_waitcnt lgkmcnt(0)
	v_add_f32_e32 v149, v69, v149
	v_cndmask_b32_e32 v147, v162, v149, vcc
	v_max3_f32 v150, v148, v146, v147
	v_add_u32_e32 v148, 0x1b0, v141
	v_max_i32_e32 v149, 31, v148
	v_subrev_u32_e32 v149, 31, v149
	v_min_u32_e32 v149, 0x1ff, v149
	v_lshl_add_u32 v149, v149, 2, s0
	ds_read_b32 v149, v149
	v_cmp_lt_i32_e32 vcc, 30, v148
	s_or_b64 vcc, s[6:7], vcc
	s_waitcnt lgkmcnt(0)
	v_add_f32_e32 v149, v70, v149
	v_cndmask_b32_e32 v148, v162, v149, vcc
	v_add_u32_e32 v149, 0x1a0, v141
	v_max_i32_e32 v151, 31, v149
	v_subrev_u32_e32 v151, 31, v151
	v_min_u32_e32 v151, 0x1ff, v151
	v_lshl_add_u32 v151, v151, 2, s0
	ds_read_b32 v151, v151
	v_cmp_lt_i32_e32 vcc, 30, v149
	s_or_b64 vcc, s[6:7], vcc
	s_waitcnt lgkmcnt(0)
	v_add_f32_e32 v151, v71, v151
	v_cndmask_b32_e32 v149, v162, v151, vcc
	v_max3_f32 v152, v150, v148, v149
	v_add_u32_e32 v150, 0x190, v141
	v_max_i32_e32 v151, 31, v150
	v_subrev_u32_e32 v151, 31, v151
	v_min_u32_e32 v151, 0x1ff, v151
	v_lshl_add_u32 v151, v151, 2, s0
	ds_read_b32 v151, v151
	v_cmp_lt_i32_e32 vcc, 30, v150
	s_or_b64 vcc, s[6:7], vcc
	s_waitcnt lgkmcnt(0)
	v_add_f32_e32 v151, v72, v151
	v_cndmask_b32_e32 v150, v162, v151, vcc
	v_add_u32_e32 v151, 0x180, v141
	v_max_i32_e32 v153, 31, v151
	v_subrev_u32_e32 v153, 31, v153
	v_min_u32_e32 v153, 0x1ff, v153
	v_lshl_add_u32 v153, v153, 2, s0
	ds_read_b32 v153, v153
	v_cmp_lt_i32_e32 vcc, 30, v151
	s_or_b64 vcc, s[6:7], vcc
	s_waitcnt lgkmcnt(0)
	v_add_f32_e32 v153, v73, v153
	v_cndmask_b32_e32 v151, v162, v153, vcc
	v_max3_f32 v154, v152, v150, v151
	v_add_u32_e32 v152, 0xf0, v141
	v_max_i32_e32 v153, 31, v152
	v_subrev_u32_e32 v153, 31, v153
	v_min_u32_e32 v153, 0x1ff, v153
	v_lshl_add_u32 v153, v153, 2, s0
	ds_read_b32 v153, v153
	v_cmp_lt_i32_e32 vcc, 30, v152
	s_or_b64 vcc, s[6:7], vcc
	s_waitcnt lgkmcnt(0)
	v_add_f32_e32 v153, v74, v153
	v_cndmask_b32_e32 v152, v162, v153, vcc
	v_add_u32_e32 v153, 0xe0, v141
	v_max_i32_e32 v155, 31, v153
	v_subrev_u32_e32 v155, 31, v155
	v_min_u32_e32 v155, 0x1ff, v155
	v_lshl_add_u32 v155, v155, 2, s0
	ds_read_b32 v155, v155
	v_cmp_lt_i32_e32 vcc, 30, v153
	s_or_b64 vcc, s[6:7], vcc
	s_waitcnt lgkmcnt(0)
	v_add_f32_e32 v155, v75, v155
	v_cndmask_b32_e32 v153, v162, v155, vcc
	v_max3_f32 v156, v154, v152, v153
	v_add_u32_e32 v154, 0xd0, v141
	v_max_i32_e32 v155, 31, v154
	v_subrev_u32_e32 v155, 31, v155
	v_min_u32_e32 v155, 0x1ff, v155
	v_lshl_add_u32 v155, v155, 2, s0
	ds_read_b32 v155, v155
	v_cmp_lt_i32_e32 vcc, 30, v154
	s_or_b64 vcc, s[6:7], vcc
	s_waitcnt lgkmcnt(0)
	v_add_f32_e32 v155, v76, v155
	v_cndmask_b32_e32 v154, v162, v155, vcc
	v_add_u32_e32 v155, 0xc0, v141
	v_max_i32_e32 v157, 31, v155
	v_subrev_u32_e32 v157, 31, v157
	v_min_u32_e32 v157, 0x1ff, v157
	v_lshl_add_u32 v157, v157, 2, s0
	ds_read_b32 v157, v157
	v_cmp_lt_i32_e32 vcc, 30, v155
	s_or_b64 vcc, s[6:7], vcc
	s_waitcnt lgkmcnt(0)
	v_add_f32_e32 v157, v77, v157
	v_cndmask_b32_e32 v155, v162, v157, vcc
	v_max3_f32 v158, v156, v154, v155
	v_add_u32_e32 v156, 0xb0, v141
	v_max_i32_e32 v157, 31, v156
	v_subrev_u32_e32 v157, 31, v157
	v_min_u32_e32 v157, 0x1ff, v157
	v_lshl_add_u32 v157, v157, 2, s0
	ds_read_b32 v157, v157
	v_cmp_lt_i32_e32 vcc, 30, v156
	s_or_b64 vcc, s[6:7], vcc
	s_waitcnt lgkmcnt(0)
	v_add_f32_e32 v157, v78, v157
	v_cndmask_b32_e32 v156, v162, v157, vcc
	v_add_u32_e32 v157, 0xa0, v141
	v_max_i32_e32 v159, 31, v157
	v_subrev_u32_e32 v159, 31, v159
	v_min_u32_e32 v159, 0x1ff, v159
	v_lshl_add_u32 v159, v159, 2, s0
	ds_read_b32 v159, v159
	v_cmp_lt_i32_e32 vcc, 30, v157
	s_or_b64 vcc, s[6:7], vcc
	s_waitcnt lgkmcnt(0)
	v_add_f32_e32 v159, v79, v159
	v_cndmask_b32_e32 v157, v162, v159, vcc
	v_max3_f32 v178, v158, v156, v157
	v_add_u32_e32 v158, 0x90, v141
	v_max_i32_e32 v159, 31, v158
	v_subrev_u32_e32 v159, 31, v159
	v_min_u32_e32 v159, 0x1ff, v159
	v_lshl_add_u32 v159, v159, 2, s0
	ds_read_b32 v159, v159
	v_cmp_lt_i32_e32 vcc, 30, v158
	s_or_b64 vcc, s[6:7], vcc
	v_add_u32_e32 v141, 0x80, v141
	s_waitcnt lgkmcnt(0)
	v_add_f32_e32 v159, v80, v159
	v_cndmask_b32_e32 v158, v162, v159, vcc
	v_max_i32_e32 v159, 31, v141
	v_subrev_u32_e32 v159, 31, v159
	v_min_u32_e32 v159, 0x1ff, v159
	v_lshl_add_u32 v159, v159, 2, s0
	ds_read_b32 v159, v159
	v_cmp_lt_i32_e32 vcc, 30, v141
	s_or_b64 vcc, s[6:7], vcc
	s_mov_b64 s[0:1], 0
	s_waitcnt lgkmcnt(0)
	v_add_f32_e32 v159, v81, v159
	v_cndmask_b32_e32 v159, v162, v159, vcc
	v_max3_f32 v178, v178, v158, v159

.LBB0_641:
	s_cmp_lg_u32 s6, 0
	s_cbranch_scc1 .Llean641
	v_sub_f32_e32 v67, v144, v176
	v_exp_f32_e32 v67, v67
	v_sub_f32_e32 v68, v145, v176
	v_cmp_lt_f32_e32 vcc, s49, v144
	v_exp_f32_e32 v68, v68
	s_or_b64 vcc, s[6:7], vcc
	v_sub_f32_e32 v70, v146, v176
	v_cndmask_b32_e32 v67, 0, v67, vcc
	v_cmp_lt_f32_e32 vcc, s49, v145
	v_exp_f32_e32 v70, v70
	s_or_b64 vcc, s[6:7], vcc
	v_sub_f32_e32 v71, v147, v176
	v_cndmask_b32_e32 v68, 0, v68, vcc
	v_cmp_lt_f32_e32 vcc, s49, v146
	v_exp_f32_e32 v71, v71
	s_or_b64 vcc, s[6:7], vcc
	v_sub_f32_e32 v72, v148, v176
	v_cndmask_b32_e32 v70, 0, v70, vcc
	v_cmp_lt_f32_e32 vcc, s49, v147
	v_exp_f32_e32 v72, v72
	s_or_b64 vcc, s[6:7], vcc
	v_sub_f32_e32 v73, v149, v176
	v_cndmask_b32_e32 v71, 0, v71, vcc
	v_cmp_lt_f32_e32 vcc, s49, v148
	v_exp_f32_e32 v73, v73
	s_or_b64 vcc, s[6:7], vcc
	v_sub_f32_e32 v74, v150, v176
	v_cndmask_b32_e32 v72, 0, v72, vcc
	v_cmp_lt_f32_e32 vcc, s49, v149
	v_exp_f32_e32 v74, v74
	s_or_b64 vcc, s[6:7], vcc
	v_sub_f32_e32 v75, v151, v176
	v_cndmask_b32_e32 v73, 0, v73, vcc
	v_cmp_lt_f32_e32 vcc, s49, v150
	v_exp_f32_e32 v75, v75
	s_or_b64 vcc, s[6:7], vcc
	v_sub_f32_e32 v76, v152, v176
	v_cndmask_b32_e32 v74, 0, v74, vcc
	v_cmp_lt_f32_e32 vcc, s49, v151
	v_exp_f32_e32 v76, v76
	s_or_b64 vcc, s[6:7], vcc
	v_sub_f32_e32 v77, v153, v176
	v_cndmask_b32_e32 v75, 0, v75, vcc
	v_cmp_lt_f32_e32 vcc, s49, v152
	v_exp_f32_e32 v77, v77
	s_or_b64 vcc, s[6:7], vcc
	v_sub_f32_e32 v78, v154, v176
	v_add_f32_e32 v69, 0, v67
	v_cndmask_b32_e32 v76, 0, v76, vcc
	v_cmp_lt_f32_e32 vcc, s49, v153
	v_exp_f32_e32 v78, v78
	v_add_f32_e32 v69, v68, v69
	s_or_b64 vcc, s[6:7], vcc
	v_sub_f32_e32 v79, v155, v176
	v_add_f32_e32 v69, v70, v69
	v_cndmask_b32_e32 v77, 0, v77, vcc
	v_cmp_lt_f32_e32 vcc, s49, v154
	v_exp_f32_e32 v79, v79
	v_add_f32_e32 v69, v71, v69
	s_or_b64 vcc, s[6:7], vcc
	v_sub_f32_e32 v80, v156, v176
	v_add_f32_e32 v69, v72, v69
	v_cndmask_b32_e32 v78, 0, v78, vcc
	v_cmp_lt_f32_e32 vcc, s49, v155
	v_exp_f32_e32 v80, v80
	v_add_f32_e32 v69, v73, v69
	s_or_b64 vcc, s[6:7], vcc
	v_sub_f32_e32 v81, v157, v176
	v_add_f32_e32 v69, v74, v69
	v_cndmask_b32_e32 v79, 0, v79, vcc
	v_cmp_lt_f32_e32 vcc, s49, v156
	v_exp_f32_e32 v81, v81
	v_add_f32_e32 v69, v75, v69
	s_or_b64 vcc, s[6:7], vcc
	v_sub_f32_e32 v141, v158, v176
	v_add_f32_e32 v69, v76, v69
	v_cndmask_b32_e32 v80, 0, v80, vcc
	v_cmp_lt_f32_e32 vcc, s49, v157
	v_exp_f32_e32 v141, v141
	v_add_f32_e32 v69, v77, v69
	s_or_b64 vcc, s[6:7], vcc
	v_sub_f32_e32 v144, v159, v176
	v_add_f32_e32 v69, v78, v69
	v_cndmask_b32_e32 v81, 0, v81, vcc
	v_cmp_lt_f32_e32 vcc, s49, v158
	v_exp_f32_e32 v144, v144
	v_add_f32_e32 v69, v79, v69
	s_or_b64 vcc, s[6:7], vcc
	v_add_f32_e32 v69, v80, v69
	v_cndmask_b32_e32 v141, 0, v141, vcc
	v_cmp_lt_f32_e32 vcc, s49, v159
	v_add_f32_e32 v69, v81, v69
	s_or_b64 vcc, s[6:7], vcc
	v_add_f32_e32 v69, v141, v69
	v_cndmask_b32_e32 v144, 0, v144, vcc
	v_add_f32_e32 v145, v144, v69
	s_branch .Ljoin641
.Llean641:
	v_sub_f32_e32 v67, v144, v176
	v_exp_f32_e32 v67, v67
	v_sub_f32_e32 v68, v145, v176
	v_exp_f32_e32 v68, v68
	v_sub_f32_e32 v70, v146, v176
	v_exp_f32_e32 v70, v70
	v_sub_f32_e32 v71, v147, v176
	v_exp_f32_e32 v71, v71
	v_sub_f32_e32 v72, v148, v176
	v_exp_f32_e32 v72, v72
	v_sub_f32_e32 v73, v149, v176
	v_exp_f32_e32 v73, v73
	v_sub_f32_e32 v74, v150, v176
	v_exp_f32_e32 v74, v74
	v_sub_f32_e32 v75, v151, v176
	v_exp_f32_e32 v75, v75
	v_sub_f32_e32 v76, v152, v176
	v_exp_f32_e32 v76, v76
	v_sub_f32_e32 v77, v153, v176
	v_exp_f32_e32 v77, v77
	v_sub_f32_e32 v78, v154, v176
	v_add_f32_e32 v69, 0, v67
	v_exp_f32_e32 v78, v78
	v_add_f32_e32 v69, v68, v69
	v_sub_f32_e32 v79, v155, v176
	v_add_f32_e32 v69, v70, v69
	v_exp_f32_e32 v79, v79
	v_add_f32_e32 v69, v71, v69
	v_sub_f32_e32 v80, v156, v176
	v_add_f32_e32 v69, v72, v69
	v_exp_f32_e32 v80, v80
	v_add_f32_e32 v69, v73, v69
	v_sub_f32_e32 v81, v157, v176
	v_add_f32_e32 v69, v74, v69
	v_exp_f32_e32 v81, v81
	v_add_f32_e32 v69, v75, v69
	v_sub_f32_e32 v141, v158, v176
	v_add_f32_e32 v69, v76, v69
	v_exp_f32_e32 v141, v141
	v_add_f32_e32 v69, v77, v69
	v_sub_f32_e32 v144, v159, v176
	v_add_f32_e32 v69, v78, v69
	v_exp_f32_e32 v144, v144
	v_add_f32_e32 v69, v79, v69
	v_add_f32_e32 v69, v80, v69
	v_add_f32_e32 v69, v81, v69
	v_add_f32_e32 v69, v141, v69
	v_add_f32_e32 v145, v144, v69
.Ljoin641:
	v_cvt_pk_bf16_f32 v68, v67, v68
	v_cvt_pk_bf16_f32 v69, v70, v71
	v_cvt_pk_bf16_f32 v70, v72, v73
	v_cvt_pk_bf16_f32 v71, v74, v75
	v_cvt_pk_bf16_f32 v72, v76, v77
	v_cvt_pk_bf16_f32 v73, v78, v79
	v_cvt_pk_bf16_f32 v74, v80, v81
	v_cvt_pk_bf16_f32 v75, v141, v144
	ds_read_b128 v[212:215], v143 offset:34880
	ds_read_b128 v[216:219], v143 offset:34912
	ds_read_b128 v[220:223], v143 offset:39488
	ds_read_b128 v[224:227], v143 offset:39520
	ds_read_b128 v[228:231], v143 offset:44096
	ds_read_b128 v[236:239], v143 offset:44128
	ds_read_b128 v[240:243], v143 offset:48704
	ds_read_b128 v[244:247], v143 offset:48736
	v_add_f32_e32 v177, v66, v145
	s_waitcnt lgkmcnt(7)
	v_mfma_f32_32x32x16_bf16 v[50:65], v[212:215], v[68:71], v[50:65]
	s_waitcnt lgkmcnt(6)
	v_mfma_f32_32x32x16_bf16 v[50:65], v[216:219], v[72:75], v[50:65]
	s_waitcnt lgkmcnt(5)
	v_mfma_f32_32x32x16_bf16 v[34:49], v[220:223], v[68:71], v[34:49]
	s_waitcnt lgkmcnt(4)
	v_mfma_f32_32x32x16_bf16 v[34:49], v[224:227], v[72:75], v[34:49]
	s_waitcnt lgkmcnt(3)
	v_mfma_f32_32x32x16_bf16 v[18:33], v[228:231], v[68:71], v[18:33]
	s_waitcnt lgkmcnt(2)
	v_mfma_f32_32x32x16_bf16 v[18:33], v[236:239], v[72:75], v[18:33]
	s_waitcnt lgkmcnt(1)
	v_mfma_f32_32x32x16_bf16 v[2:17], v[240:243], v[68:71], v[2:17]
	s_waitcnt lgkmcnt(0)
	v_mfma_f32_32x32x16_bf16 v[2:17], v[244:247], v[72:75], v[2:17]

.LBB0_653:
	s_and_b32 s57, s55, 1
	s_cmp_gt_u32 s9, s33
	s_cselect_b64 s[2:3], -1, 0
	s_add_i32 s0, s9, 63
	s_cmp_lt_i32 s0, s51
	s_cselect_b64 s[6:7], -1, 0
	s_or_b64 s[2:3], s[2:3], s[6:7]
	s_and_b64 vcc, exec, s[2:3]
	s_cbranch_vccnz .LBB0_667
	s_mul_i32 s1, s57, 0x4400
	v_add_u32_e32 v174, s1, v170
	ds_read_b128 v[212:215], v174
	ds_read_b128 v[216:219], v174 offset:32
	ds_read_b128 v[220:223], v174 offset:64
	ds_read_b128 v[224:227], v174 offset:96
	ds_read_b128 v[228:231], v174 offset:128
	ds_read_b128 v[236:239], v174 offset:160
	ds_read_b128 v[240:243], v174 offset:192
	ds_read_b128 v[244:247], v174 offset:224
	s_cmp_le_u32 s0, s26
	s_cselect_b64 s[2:3], -1, 0
	s_cmp_ge_i32 s9, s54
	s_cselect_b64 s[6:7], -1, 0
	s_and_b64 s[6:7], s[2:3], s[6:7]
	s_cmp_lt_i32 s0, s29
	s_cselect_b64 s[0:1], -1, 0
	s_and_b64 s[0:1], s[6:7], s[0:1]
	s_mov_b64 s[2:3], -1
	s_waitcnt lgkmcnt(7)
	v_mfma_f32_32x32x16_bf16 v[80:95], v[212:215], v[96:99], 0
	s_waitcnt lgkmcnt(6)
	v_mfma_f32_32x32x16_bf16 v[80:95], v[216:219], v[100:103], v[80:95]
	s_waitcnt lgkmcnt(5)
	v_mfma_f32_32x32x16_bf16 v[80:95], v[220:223], v[104:107], v[80:95]
	s_waitcnt lgkmcnt(4)
	v_mfma_f32_32x32x16_bf16 v[80:95], v[224:227], v[108:111], v[80:95]
	s_waitcnt lgkmcnt(3)
	v_mfma_f32_32x32x16_bf16 v[80:95], v[228:231], v[112:115], v[80:95]
	s_waitcnt lgkmcnt(2)
	v_mfma_f32_32x32x16_bf16 v[80:95], v[236:239], v[116:119], v[80:95]
	s_waitcnt lgkmcnt(1)
	v_mfma_f32_32x32x16_bf16 v[80:95], v[240:243], v[120:123], v[80:95]
	s_waitcnt lgkmcnt(0)
	v_mfma_f32_32x32x16_bf16 v[80:95], v[244:247], v[124:127], v[80:95]
	s_and_b64 vcc, exec, s[0:1]
	s_cbranch_vccnz .LBB0_656
	v_add_u32_e32 v0, 55, v171
	v_med3_i32 v2, v0, 0, v164
	v_lshl_add_u32 v2, v2, 2, s34
	v_cmp_gt_u32_e32 vcc, s44, v0
	v_add_u32_e32 v0, 54, v171
	ds_read_b32 v2, v2
	v_med3_i32 v3, v0, 0, v164
	v_lshl_add_u32 v3, v3, 2, s34
	v_add_u32_e32 v4, 53, v171
	ds_read_b32 v3, v3
	v_med3_i32 v5, v4, 0, v164
	v_lshl_add_u32 v5, v5, 2, s34
	ds_read_b32 v5, v5
	s_waitcnt lgkmcnt(2)
	v_add_f32_e32 v2, v80, v2
	s_or_b64 vcc, vcc, s[6:7]
	v_cndmask_b32_e32 v2, v162, v2, vcc
	v_cmp_gt_u32_e32 vcc, s44, v0
	s_waitcnt lgkmcnt(1)
	v_add_f32_e32 v3, v81, v3
	s_or_b64 vcc, s[6:7], vcc
	v_cndmask_b32_e32 v3, v162, v3, vcc
	v_cmp_gt_u32_e32 vcc, s44, v4
	s_waitcnt lgkmcnt(0)
	v_add_f32_e32 v5, v82, v5
	s_or_b64 vcc, s[6:7], vcc
	v_cndmask_b32_e32 v4, v162, v5, vcc
	v_add_u32_e32 v5, 52, v171
	v_med3_i32 v6, v5, 0, v164
	v_lshl_add_u32 v6, v6, 2, s34
	ds_read_b32 v6, v6
	v_cmp_gt_u32_e32 vcc, s44, v5
	s_or_b64 vcc, s[6:7], vcc
	v_max3_f32 v0, v2, s47, v3
	s_mov_b64 s[2:3], 0
	s_waitcnt lgkmcnt(0)
	v_add_f32_e32 v6, v83, v6
	v_cndmask_b32_e32 v5, v162, v6, vcc
	v_add_u32_e32 v6, 51, v171
	v_med3_i32 v7, v6, 0, v164
	v_lshl_add_u32 v7, v7, 2, s34
	ds_read_b32 v7, v7
	v_cmp_gt_u32_e32 vcc, s44, v6
	s_or_b64 vcc, s[6:7], vcc
	v_max3_f32 v0, v0, v4, v5
	s_waitcnt lgkmcnt(0)
	v_add_f32_e32 v7, v84, v7
	v_cndmask_b32_e32 v6, v162, v7, vcc
	v_add_u32_e32 v7, 50, v171
	v_med3_i32 v8, v7, 0, v164
	v_lshl_add_u32 v8, v8, 2, s34
	ds_read_b32 v8, v8
	v_cmp_gt_u32_e32 vcc, s44, v7
	s_or_b64 vcc, s[6:7], vcc
	s_waitcnt lgkmcnt(0)
	v_add_f32_e32 v8, v85, v8
	v_cndmask_b32_e32 v7, v162, v8, vcc
	v_add_u32_e32 v8, 49, v171
	v_med3_i32 v9, v8, 0, v164
	v_lshl_add_u32 v9, v9, 2, s34
	ds_read_b32 v9, v9
	v_cmp_gt_u32_e32 vcc, s44, v8
	s_or_b64 vcc, s[6:7], vcc
	v_max3_f32 v0, v0, v6, v7
	s_waitcnt lgkmcnt(0)
	v_add_f32_e32 v9, v86, v9
	v_cndmask_b32_e32 v8, v162, v9, vcc
	v_add_u32_e32 v9, 48, v171
	v_med3_i32 v10, v9, 0, v164
	v_lshl_add_u32 v10, v10, 2, s34
	ds_read_b32 v10, v10
	v_cmp_gt_u32_e32 vcc, s44, v9
	s_or_b64 vcc, s[6:7], vcc
	s_waitcnt lgkmcnt(0)
	v_add_f32_e32 v10, v87, v10
	v_cndmask_b32_e32 v9, v162, v10, vcc
	v_add_u32_e32 v10, 39, v171
	v_med3_i32 v11, v10, 0, v164
	v_lshl_add_u32 v11, v11, 2, s34
	ds_read_b32 v11, v11
	v_cmp_gt_u32_e32 vcc, s44, v10
	s_or_b64 vcc, vcc, s[6:7]
	v_max3_f32 v0, v0, v8, v9
	s_waitcnt lgkmcnt(0)
	v_add_f32_e32 v11, v88, v11
	v_cndmask_b32_e32 v10, v162, v11, vcc
	v_add_u32_e32 v11, 38, v171
	v_med3_i32 v12, v11, 0, v164
	v_lshl_add_u32 v12, v12, 2, s34
	ds_read_b32 v12, v12
	v_cmp_gt_u32_e32 vcc, s44, v11
	s_or_b64 vcc, s[6:7], vcc
	s_waitcnt lgkmcnt(0)
	v_add_f32_e32 v12, v89, v12
	v_cndmask_b32_e32 v11, v162, v12, vcc
	v_add_u32_e32 v12, 37, v171
	v_med3_i32 v13, v12, 0, v164
	v_lshl_add_u32 v13, v13, 2, s34
	ds_read_b32 v13, v13
	v_cmp_gt_u32_e32 vcc, s44, v12
	s_or_b64 vcc, s[6:7], vcc
	v_max3_f32 v0, v0, v10, v11
	s_waitcnt lgkmcnt(0)
	v_add_f32_e32 v13, v90, v13
	v_cndmask_b32_e32 v12, v162, v13, vcc
	v_add_u32_e32 v13, 36, v171
	v_med3_i32 v14, v13, 0, v164
	v_lshl_add_u32 v14, v14, 2, s34
	ds_read_b32 v14, v14
	v_cmp_gt_u32_e32 vcc, s44, v13
	s_or_b64 vcc, s[6:7], vcc
	s_waitcnt lgkmcnt(0)
	v_add_f32_e32 v14, v91, v14
	v_cndmask_b32_e32 v13, v162, v14, vcc
	v_add_u32_e32 v14, 35, v171
	v_med3_i32 v15, v14, 0, v164
	v_lshl_add_u32 v15, v15, 2, s34
	ds_read_b32 v15, v15
	v_cmp_gt_u32_e32 vcc, s44, v14
	s_or_b64 vcc, s[6:7], vcc
	v_max3_f32 v0, v0, v12, v13
	s_waitcnt lgkmcnt(0)
	v_add_f32_e32 v15, v92, v15
	v_cndmask_b32_e32 v14, v162, v15, vcc
	v_add_u32_e32 v15, 34, v171
	v_med3_i32 v156, v15, 0, v164
	v_lshl_add_u32 v156, v156, 2, s34
	ds_read_b32 v156, v156
	v_cmp_gt_u32_e32 vcc, s44, v15
	s_or_b64 vcc, s[6:7], vcc
	s_waitcnt lgkmcnt(0)
	v_add_f32_e32 v156, v93, v156
	v_cndmask_b32_e32 v15, v162, v156, vcc
	v_add_u32_e32 v156, 33, v171
	v_med3_i32 v157, v156, 0, v164
	v_lshl_add_u32 v157, v157, 2, s34
	ds_read_b32 v157, v157
	v_cmp_gt_u32_e32 vcc, s44, v156
	s_or_b64 vcc, s[6:7], vcc
	v_max3_f32 v0, v0, v14, v15
	s_waitcnt lgkmcnt(0)
	v_add_f32_e32 v157, v94, v157
	v_cndmask_b32_e32 v156, v162, v157, vcc
	v_add_u32_e32 v157, 32, v171
	v_med3_i32 v175, v157, 0, v164
	v_lshl_add_u32 v175, v175, 2, s34
	ds_read_b32 v175, v175
	v_cmp_gt_u32_e32 vcc, s44, v157
	s_or_b64 vcc, s[6:7], vcc
	s_waitcnt lgkmcnt(0)
	v_add_f32_e32 v175, v95, v175
	v_cndmask_b32_e32 v157, v162, v175, vcc
	v_max3_f32 v0, v0, v156, v157

.LBB0_660:
	s_cmp_lg_u32 s6, 0
	s_cbranch_scc1 .Llean660
	v_sub_f32_e32 v0, v2, v172
	v_exp_f32_e32 v0, v0
	v_cmp_lt_f32_e32 vcc, s49, v2
	v_sub_f32_e32 v2, v3, v172
	v_exp_f32_e32 v2, v2
	s_or_b64 vcc, s[6:7], vcc
	v_cndmask_b32_e32 v175, 0, v0, vcc
	v_cmp_lt_f32_e32 vcc, s49, v3
	v_sub_f32_e32 v0, v4, v172
	s_or_b64 vcc, s[6:7], vcc
	v_exp_f32_e32 v0, v0
	v_cndmask_b32_e32 v176, 0, v2, vcc
	v_sub_f32_e32 v2, v5, v172
	v_cmp_lt_f32_e32 vcc, s49, v4
	v_exp_f32_e32 v2, v2
	s_or_b64 vcc, s[6:7], vcc
	v_cndmask_b32_e32 v177, 0, v0, vcc
	v_cmp_lt_f32_e32 vcc, s49, v5
	v_sub_f32_e32 v0, v6, v172
	s_or_b64 vcc, s[6:7], vcc
	v_exp_f32_e32 v0, v0
	v_cndmask_b32_e32 v178, 0, v2, vcc
	v_sub_f32_e32 v2, v7, v172
	v_cmp_lt_f32_e32 vcc, s49, v6
	v_exp_f32_e32 v2, v2
	s_or_b64 vcc, s[6:7], vcc
	v_cndmask_b32_e32 v179, 0, v0, vcc
	v_cmp_lt_f32_e32 vcc, s49, v7
	v_sub_f32_e32 v0, v8, v172
	s_or_b64 vcc, s[6:7], vcc
	v_exp_f32_e32 v0, v0
	v_cndmask_b32_e32 v180, 0, v2, vcc
	v_sub_f32_e32 v2, v9, v172
	v_cmp_lt_f32_e32 vcc, s49, v8
	v_exp_f32_e32 v2, v2
	s_or_b64 vcc, s[6:7], vcc
	v_cndmask_b32_e32 v181, 0, v0, vcc
	v_cmp_lt_f32_e32 vcc, s49, v9
	v_sub_f32_e32 v0, v10, v172
	s_or_b64 vcc, s[6:7], vcc
	v_exp_f32_e32 v0, v0
	v_cndmask_b32_e32 v183, 0, v2, vcc
	v_sub_f32_e32 v2, v11, v172
	v_cmp_lt_f32_e32 vcc, s49, v10
	v_exp_f32_e32 v2, v2
	s_or_b64 vcc, s[6:7], vcc
	v_cndmask_b32_e32 v184, 0, v0, vcc
	v_cmp_lt_f32_e32 vcc, s49, v11
	v_sub_f32_e32 v0, v12, v172
	s_or_b64 vcc, s[6:7], vcc
	v_exp_f32_e32 v0, v0
	v_cndmask_b32_e32 v185, 0, v2, vcc
	v_sub_f32_e32 v2, v13, v172
	v_cmp_lt_f32_e32 vcc, s49, v12
	v_exp_f32_e32 v2, v2
	s_or_b64 vcc, s[6:7], vcc
	v_cndmask_b32_e32 v186, 0, v0, vcc
	v_cmp_lt_f32_e32 vcc, s49, v13
	v_sub_f32_e32 v0, v14, v172
	s_or_b64 vcc, s[6:7], vcc
	v_exp_f32_e32 v0, v0
	v_cndmask_b32_e32 v187, 0, v2, vcc
	v_sub_f32_e32 v2, v15, v172
	v_cmp_lt_f32_e32 vcc, s49, v14
	v_exp_f32_e32 v2, v2
	s_or_b64 vcc, s[6:7], vcc
	v_cndmask_b32_e32 v188, 0, v0, vcc
	v_cmp_lt_f32_e32 vcc, s49, v15
	v_sub_f32_e32 v0, v156, v172
	s_or_b64 vcc, s[6:7], vcc
	v_exp_f32_e32 v0, v0
	v_cndmask_b32_e32 v189, 0, v2, vcc
	v_sub_f32_e32 v2, v157, v172
	v_cmp_lt_f32_e32 vcc, s49, v156
	v_exp_f32_e32 v2, v2
	s_or_b64 vcc, s[6:7], vcc
	v_cndmask_b32_e32 v190, 0, v0, vcc
	v_cmp_lt_f32_e32 vcc, s49, v157
	s_or_b64 vcc, s[6:7], vcc
	s_xor_b64 s[0:1], s[0:1], -1
	v_cndmask_b32_e32 v191, 0, v2, vcc
	s_branch .Ljoin660
.Llean660:
	v_sub_f32_e32 v0, v2, v172
	v_exp_f32_e32 v0, v0
	v_sub_f32_e32 v2, v3, v172
	v_exp_f32_e32 v2, v2
	v_mov_b32_e32 v175, v0
	v_sub_f32_e32 v0, v4, v172
	v_exp_f32_e32 v0, v0
	v_mov_b32_e32 v176, v2
	v_sub_f32_e32 v2, v5, v172
	v_exp_f32_e32 v2, v2
	v_mov_b32_e32 v177, v0
	v_sub_f32_e32 v0, v6, v172
	v_exp_f32_e32 v0, v0
	v_mov_b32_e32 v178, v2
	v_sub_f32_e32 v2, v7, v172
	v_exp_f32_e32 v2, v2
	v_mov_b32_e32 v179, v0
	v_sub_f32_e32 v0, v8, v172
	v_exp_f32_e32 v0, v0
	v_mov_b32_e32 v180, v2
	v_sub_f32_e32 v2, v9, v172
	v_exp_f32_e32 v2, v2
	v_mov_b32_e32 v181, v0
	v_sub_f32_e32 v0, v10, v172
	v_exp_f32_e32 v0, v0
	v_mov_b32_e32 v183, v2
	v_sub_f32_e32 v2, v11, v172
	v_exp_f32_e32 v2, v2
	v_mov_b32_e32 v184, v0
	v_sub_f32_e32 v0, v12, v172
	v_exp_f32_e32 v0, v0
	v_mov_b32_e32 v185, v2
	v_sub_f32_e32 v2, v13, v172
	v_exp_f32_e32 v2, v2
	v_mov_b32_e32 v186, v0
	v_sub_f32_e32 v0, v14, v172
	v_exp_f32_e32 v0, v0
	v_mov_b32_e32 v187, v2
	v_sub_f32_e32 v2, v15, v172
	v_exp_f32_e32 v2, v2
	v_mov_b32_e32 v188, v0
	v_sub_f32_e32 v0, v156, v172
	v_exp_f32_e32 v0, v0
	v_mov_b32_e32 v189, v2
	v_sub_f32_e32 v2, v157, v172
	v_exp_f32_e32 v2, v2
	v_mov_b32_e32 v190, v0
	s_xor_b64 s[0:1], s[0:1], -1
	v_mov_b32_e32 v191, v2
.Ljoin660:
	v_cvt_pk_bf16_f32 v2, v175, v176
	v_cvt_pk_bf16_f32 v3, v177, v178
	v_cvt_pk_bf16_f32 v4, v179, v180
	v_cvt_pk_bf16_f32 v5, v181, v183
	v_cvt_pk_bf16_f32 v6, v184, v185
	v_cvt_pk_bf16_f32 v7, v186, v187
	v_cvt_pk_bf16_f32 v8, v188, v189
	v_cvt_pk_bf16_f32 v9, v190, v191
	s_mul_i32 s2, s57, 0x4800
	v_add_u32_e32 v0, s2, v169
	ds_read_b128 v[212:215], v0 offset:34816
	ds_read_b128 v[216:219], v0 offset:34848
	ds_read_b128 v[220:223], v0 offset:39424
	ds_read_b128 v[224:227], v0 offset:39456
	ds_read_b128 v[228:231], v0 offset:44032
	ds_read_b128 v[236:239], v0 offset:44064
	ds_read_b128 v[240:243], v0 offset:48640
	ds_read_b128 v[244:247], v0 offset:48672
	s_waitcnt lgkmcnt(7)
	v_mfma_f32_32x32x16_bf16 v[64:79], v[212:215], v[2:5], v[64:79]
	s_waitcnt lgkmcnt(6)
	v_mfma_f32_32x32x16_bf16 v[64:79], v[216:219], v[6:9], v[64:79]
	s_waitcnt lgkmcnt(5)
	v_mfma_f32_32x32x16_bf16 v[48:63], v[220:223], v[2:5], v[48:63]
	s_waitcnt lgkmcnt(4)
	v_mfma_f32_32x32x16_bf16 v[48:63], v[224:227], v[6:9], v[48:63]
	s_waitcnt lgkmcnt(3)
	v_mfma_f32_32x32x16_bf16 v[32:47], v[228:231], v[2:5], v[32:47]
	s_waitcnt lgkmcnt(2)
	v_mfma_f32_32x32x16_bf16 v[32:47], v[236:239], v[6:9], v[32:47]
	s_waitcnt lgkmcnt(1)
	v_mfma_f32_32x32x16_bf16 v[16:31], v[240:243], v[2:5], v[16:31]
	s_waitcnt lgkmcnt(0)
	v_mfma_f32_32x32x16_bf16 v[16:31], v[244:247], v[6:9], v[16:31]
	ds_read_b128 v[212:215], v174 offset:8704
	ds_read_b128 v[216:219], v174 offset:8736
	ds_read_b128 v[220:223], v174 offset:8768
	ds_read_b128 v[224:227], v174 offset:8800
	ds_read_b128 v[228:231], v174 offset:8832
	ds_read_b128 v[236:239], v174 offset:8864
	ds_read_b128 v[240:243], v174 offset:8896
	ds_read_b128 v[244:247], v174 offset:8928
	s_waitcnt lgkmcnt(7)
	v_mfma_f32_32x32x16_bf16 v[80:95], v[212:215], v[96:99], 0
	s_waitcnt lgkmcnt(6)
	v_mfma_f32_32x32x16_bf16 v[80:95], v[216:219], v[100:103], v[80:95]
	s_waitcnt lgkmcnt(5)
	v_mfma_f32_32x32x16_bf16 v[80:95], v[220:223], v[104:107], v[80:95]
	s_waitcnt lgkmcnt(4)
	v_mfma_f32_32x32x16_bf16 v[80:95], v[224:227], v[108:111], v[80:95]
	s_waitcnt lgkmcnt(3)
	v_mfma_f32_32x32x16_bf16 v[80:95], v[228:231], v[112:115], v[80:95]
	s_waitcnt lgkmcnt(2)
	v_mfma_f32_32x32x16_bf16 v[80:95], v[236:239], v[116:119], v[80:95]
	s_waitcnt lgkmcnt(1)
	v_mfma_f32_32x32x16_bf16 v[80:95], v[240:243], v[120:123], v[80:95]
	s_waitcnt lgkmcnt(0)
	v_mfma_f32_32x32x16_bf16 v[80:95], v[244:247], v[124:127], v[80:95]
	s_andn2_b64 vcc, exec, s[0:1]
	s_mov_b64 s[0:1], -1
	s_cbranch_vccnz .LBB0_662
	v_add_u32_e32 v2, 23, v171
	v_med3_i32 v3, v2, 0, v164
	v_lshl_add_u32 v3, v3, 2, s34
	ds_read_b32 v3, v3
	v_cmp_gt_u32_e32 vcc, s44, v2
	s_or_b64 vcc, vcc, s[6:7]
	s_mov_b64 s[0:1], 0
	s_waitcnt lgkmcnt(0)
	s_nop 0
	v_add_f32_e32 v3, v80, v3
	v_cndmask_b32_e32 v2, v162, v3, vcc
	v_add_u32_e32 v3, 22, v171
	v_med3_i32 v4, v3, 0, v164
	v_lshl_add_u32 v4, v4, 2, s34
	ds_read_b32 v4, v4
	v_cmp_gt_u32_e32 vcc, s44, v3
	s_or_b64 vcc, s[6:7], vcc
	s_waitcnt lgkmcnt(0)
	v_add_f32_e32 v4, v81, v4
	v_cndmask_b32_e32 v3, v162, v4, vcc
	v_add_u32_e32 v4, 21, v171
	v_med3_i32 v5, v4, 0, v164
	v_lshl_add_u32 v5, v5, 2, s34
	ds_read_b32 v5, v5
	v_cmp_gt_u32_e32 vcc, s44, v4
	s_or_b64 vcc, s[6:7], vcc
	v_max3_f32 v6, v2, s47, v3
	s_waitcnt lgkmcnt(0)
	v_add_f32_e32 v5, v82, v5
	v_cndmask_b32_e32 v4, v162, v5, vcc
	v_add_u32_e32 v5, 20, v171
	v_med3_i32 v7, v5, 0, v164
	v_lshl_add_u32 v7, v7, 2, s34
	ds_read_b32 v7, v7
	v_cmp_gt_u32_e32 vcc, s44, v5
	s_or_b64 vcc, s[6:7], vcc
	s_waitcnt lgkmcnt(0)
	v_add_f32_e32 v7, v83, v7
	v_cndmask_b32_e32 v5, v162, v7, vcc
	v_max3_f32 v8, v6, v4, v5
	v_add_u32_e32 v6, 19, v171
	v_med3_i32 v7, v6, 0, v164
	v_lshl_add_u32 v7, v7, 2, s34
	ds_read_b32 v7, v7
	v_cmp_gt_u32_e32 vcc, s44, v6
	s_or_b64 vcc, s[6:7], vcc
	s_waitcnt lgkmcnt(0)
	v_add_f32_e32 v7, v84, v7
	v_cndmask_b32_e32 v6, v162, v7, vcc
	v_add_u32_e32 v7, 18, v171
	v_med3_i32 v9, v7, 0, v164
	v_lshl_add_u32 v9, v9, 2, s34
	ds_read_b32 v9, v9
	v_cmp_gt_u32_e32 vcc, s44, v7
	s_or_b64 vcc, s[6:7], vcc
	s_waitcnt lgkmcnt(0)
	v_add_f32_e32 v9, v85, v9
	v_cndmask_b32_e32 v7, v162, v9, vcc
	v_max3_f32 v10, v8, v6, v7
	v_add_u32_e32 v8, 17, v171
	v_med3_i32 v9, v8, 0, v164
	v_lshl_add_u32 v9, v9, 2, s34
	ds_read_b32 v9, v9
	v_cmp_gt_u32_e32 vcc, s44, v8
	s_or_b64 vcc, s[6:7], vcc
	s_waitcnt lgkmcnt(0)
	v_add_f32_e32 v9, v86, v9
	v_cndmask_b32_e32 v8, v162, v9, vcc
	v_add_u32_e32 v9, 16, v171
	v_med3_i32 v11, v9, 0, v164
	v_lshl_add_u32 v11, v11, 2, s34
	ds_read_b32 v11, v11
	v_cmp_gt_u32_e32 vcc, s44, v9
	s_or_b64 vcc, s[6:7], vcc
	s_waitcnt lgkmcnt(0)
	v_add_f32_e32 v11, v87, v11
	v_cndmask_b32_e32 v9, v162, v11, vcc
	v_max3_f32 v12, v10, v8, v9
	v_add_u32_e32 v10, 7, v171
	v_med3_i32 v11, v10, 0, v164
	v_lshl_add_u32 v11, v11, 2, s34
	ds_read_b32 v11, v11
	v_cmp_gt_u32_e32 vcc, s44, v10
	s_or_b64 vcc, vcc, s[6:7]
	s_waitcnt lgkmcnt(0)
	v_add_f32_e32 v11, v88, v11
	v_cndmask_b32_e32 v10, v162, v11, vcc
	v_add_u32_e32 v11, 6, v171
	v_med3_i32 v13, v11, 0, v164
	v_lshl_add_u32 v13, v13, 2, s34
	ds_read_b32 v13, v13
	v_cmp_gt_u32_e32 vcc, s44, v11
	s_or_b64 vcc, s[6:7], vcc
	s_waitcnt lgkmcnt(0)
	v_add_f32_e32 v13, v89, v13
	v_cndmask_b32_e32 v11, v162, v13, vcc
	v_max3_f32 v14, v12, v10, v11
	v_add_u32_e32 v12, 5, v171
	v_med3_i32 v13, v12, 0, v164
	v_lshl_add_u32 v13, v13, 2, s34
	ds_read_b32 v13, v13
	v_cmp_gt_u32_e32 vcc, s44, v12
	s_or_b64 vcc, s[6:7], vcc
	s_waitcnt lgkmcnt(0)
	v_add_f32_e32 v13, v90, v13
	v_cndmask_b32_e32 v12, v162, v13, vcc
	v_add_u32_e32 v13, 4, v171
	v_med3_i32 v15, v13, 0, v164
	v_lshl_add_u32 v15, v15, 2, s34
	ds_read_b32 v15, v15
	v_cmp_gt_u32_e32 vcc, s44, v13
	s_or_b64 vcc, s[6:7], vcc
	s_waitcnt lgkmcnt(0)
	v_add_f32_e32 v15, v91, v15
	v_cndmask_b32_e32 v13, v162, v15, vcc
	v_max3_f32 v156, v14, v12, v13
	v_add_u32_e32 v14, 3, v171
	v_med3_i32 v15, v14, 0, v164
	v_lshl_add_u32 v15, v15, 2, s34
	ds_read_b32 v15, v15
	v_cmp_gt_u32_e32 vcc, s44, v14
	s_or_b64 vcc, s[6:7], vcc
	s_waitcnt lgkmcnt(0)
	v_add_f32_e32 v15, v92, v15
	v_cndmask_b32_e32 v14, v162, v15, vcc
	v_add_u32_e32 v15, 2, v171
	v_med3_i32 v157, v15, 0, v164
	v_lshl_add_u32 v157, v157, 2, s34
	ds_read_b32 v157, v157
	v_cmp_gt_u32_e32 vcc, s44, v15
	s_or_b64 vcc, s[6:7], vcc
	s_waitcnt lgkmcnt(0)
	v_add_f32_e32 v157, v93, v157
	v_cndmask_b32_e32 v15, v162, v157, vcc
	v_max3_f32 v174, v156, v14, v15
	v_add_u32_e32 v156, 1, v171
	v_med3_i32 v157, v156, 0, v164
	v_lshl_add_u32 v157, v157, 2, s34
	ds_read_b32 v157, v157
	v_cmp_gt_u32_e32 vcc, s44, v156
	s_or_b64 vcc, s[6:7], vcc
	s_waitcnt lgkmcnt(0)
	v_add_f32_e32 v157, v94, v157
	v_cndmask_b32_e32 v156, v162, v157, vcc
	v_med3_i32 v157, v171, 0, v164
	v_lshl_add_u32 v157, v157, 2, s34
	ds_read_b32 v157, v157
	v_cmp_gt_u32_e32 vcc, s44, v171
	s_or_b64 vcc, s[6:7], vcc
	s_waitcnt lgkmcnt(0)
	v_add_f32_e32 v157, v95, v157
	v_cndmask_b32_e32 v157, v162, v157, vcc
	v_max3_f32 v174, v174, v156, v157

.LBB0_666:
	s_cmp_lg_u32 s6, 0
	s_cbranch_scc1 .Llean666
	v_sub_f32_e32 v81, v2, v172
	v_exp_f32_e32 v81, v81
	v_cmp_lt_f32_e32 vcc, s49, v2
	v_sub_f32_e32 v2, v3, v172
	s_or_b64 vcc, s[6:7], vcc
	v_exp_f32_e32 v2, v2
	v_cndmask_b32_e32 v81, 0, v81, vcc
	v_cmp_lt_f32_e32 vcc, s49, v3
	v_sub_f32_e32 v3, v4, v172
	v_exp_f32_e32 v3, v3
	s_or_b64 vcc, s[6:7], vcc
	v_cndmask_b32_e32 v2, 0, v2, vcc
	v_cmp_lt_f32_e32 vcc, s49, v4
	v_sub_f32_e32 v4, v5, v172
	s_or_b64 vcc, s[6:7], vcc
	v_exp_f32_e32 v4, v4
	v_cndmask_b32_e32 v3, 0, v3, vcc
	v_cmp_lt_f32_e32 vcc, s49, v5
	v_sub_f32_e32 v5, v6, v172
	v_exp_f32_e32 v5, v5
	s_or_b64 vcc, s[6:7], vcc
	v_cndmask_b32_e32 v4, 0, v4, vcc
	v_cmp_lt_f32_e32 vcc, s49, v6
	v_sub_f32_e32 v6, v7, v172
	s_or_b64 vcc, s[6:7], vcc
	v_exp_f32_e32 v6, v6
	v_cndmask_b32_e32 v5, 0, v5, vcc
	v_cmp_lt_f32_e32 vcc, s49, v7
	v_sub_f32_e32 v7, v8, v172
	v_exp_f32_e32 v7, v7
	s_or_b64 vcc, s[6:7], vcc
	v_cndmask_b32_e32 v6, 0, v6, vcc
	v_cmp_lt_f32_e32 vcc, s49, v8
	v_sub_f32_e32 v8, v9, v172
	s_or_b64 vcc, s[6:7], vcc
	v_exp_f32_e32 v8, v8
	v_cndmask_b32_e32 v7, 0, v7, vcc
	v_cmp_lt_f32_e32 vcc, s49, v9
	v_sub_f32_e32 v9, v10, v172
	v_exp_f32_e32 v9, v9
	s_or_b64 vcc, s[6:7], vcc
	v_cndmask_b32_e32 v8, 0, v8, vcc
	v_cmp_lt_f32_e32 vcc, s49, v10
	v_sub_f32_e32 v10, v11, v172
	s_or_b64 vcc, s[6:7], vcc
	v_exp_f32_e32 v10, v10
	v_cndmask_b32_e32 v9, 0, v9, vcc
	v_cmp_lt_f32_e32 vcc, s49, v11
	v_sub_f32_e32 v11, v12, v172
	v_exp_f32_e32 v11, v11
	s_or_b64 vcc, s[6:7], vcc
	v_add_f32_e32 v82, 0, v81
	v_cndmask_b32_e32 v10, 0, v10, vcc
	v_cmp_lt_f32_e32 vcc, s49, v12
	v_sub_f32_e32 v12, v13, v172
	v_add_f32_e32 v82, v2, v82
	s_or_b64 vcc, s[6:7], vcc
	v_exp_f32_e32 v12, v12
	v_add_f32_e32 v82, v3, v82
	v_cndmask_b32_e32 v11, 0, v11, vcc
	v_cmp_lt_f32_e32 vcc, s49, v13
	v_sub_f32_e32 v13, v14, v172
	v_add_f32_e32 v82, v4, v82
	v_exp_f32_e32 v13, v13
	v_add_f32_e32 v82, v5, v82
	s_or_b64 vcc, s[6:7], vcc
	v_add_f32_e32 v82, v6, v82
	v_cndmask_b32_e32 v12, 0, v12, vcc
	v_cmp_lt_f32_e32 vcc, s49, v14
	v_sub_f32_e32 v14, v15, v172
	v_add_f32_e32 v82, v7, v82
	s_or_b64 vcc, s[6:7], vcc
	v_exp_f32_e32 v14, v14
	v_add_f32_e32 v82, v8, v82
	v_cndmask_b32_e32 v13, 0, v13, vcc
	v_cmp_lt_f32_e32 vcc, s49, v15
	v_sub_f32_e32 v15, v156, v172
	v_add_f32_e32 v82, v9, v82
	v_exp_f32_e32 v15, v15
	v_add_f32_e32 v82, v10, v82
	s_or_b64 vcc, s[6:7], vcc
	v_sub_f32_e32 v83, v157, v172
	v_add_f32_e32 v82, v11, v82
	v_cndmask_b32_e32 v14, 0, v14, vcc
	v_cmp_lt_f32_e32 vcc, s49, v156
	v_exp_f32_e32 v83, v83
	v_add_f32_e32 v82, v12, v82
	s_or_b64 vcc, s[6:7], vcc
	v_add_f32_e32 v82, v13, v82
	v_cndmask_b32_e32 v15, 0, v15, vcc
	v_cmp_lt_f32_e32 vcc, s49, v157
	v_add_f32_e32 v82, v14, v82
	s_or_b64 vcc, s[6:7], vcc
	v_add_f32_e32 v82, v15, v82
	v_cndmask_b32_e32 v83, 0, v83, vcc
	v_add_f32_e32 v82, v83, v82
	s_branch .Ljoin666
.Llean666:
	v_sub_f32_e32 v81, v2, v172
	v_exp_f32_e32 v81, v81
	v_sub_f32_e32 v2, v3, v172
	v_exp_f32_e32 v2, v2
	v_sub_f32_e32 v3, v4, v172
	v_exp_f32_e32 v3, v3
	v_sub_f32_e32 v4, v5, v172
	v_exp_f32_e32 v4, v4
	v_sub_f32_e32 v5, v6, v172
	v_exp_f32_e32 v5, v5
	v_sub_f32_e32 v6, v7, v172
	v_exp_f32_e32 v6, v6
	v_sub_f32_e32 v7, v8, v172
	v_exp_f32_e32 v7, v7
	v_sub_f32_e32 v8, v9, v172
	v_exp_f32_e32 v8, v8
	v_sub_f32_e32 v9, v10, v172
	v_exp_f32_e32 v9, v9
	v_sub_f32_e32 v10, v11, v172
	v_exp_f32_e32 v10, v10
	v_sub_f32_e32 v11, v12, v172
	v_exp_f32_e32 v11, v11
	v_add_f32_e32 v82, 0, v81
	v_sub_f32_e32 v12, v13, v172
	v_add_f32_e32 v82, v2, v82
	v_exp_f32_e32 v12, v12
	v_add_f32_e32 v82, v3, v82
	v_sub_f32_e32 v13, v14, v172
	v_add_f32_e32 v82, v4, v82
	v_exp_f32_e32 v13, v13
	v_add_f32_e32 v82, v5, v82
	v_add_f32_e32 v82, v6, v82
	v_sub_f32_e32 v14, v15, v172
	v_add_f32_e32 v82, v7, v82
	v_exp_f32_e32 v14, v14
	v_add_f32_e32 v82, v8, v82
	v_sub_f32_e32 v15, v156, v172
	v_add_f32_e32 v82, v9, v82
	v_exp_f32_e32 v15, v15
	v_add_f32_e32 v82, v10, v82
	v_sub_f32_e32 v83, v157, v172
	v_add_f32_e32 v82, v11, v82
	v_exp_f32_e32 v83, v83
	v_add_f32_e32 v82, v12, v82
	v_add_f32_e32 v82, v13, v82
	v_add_f32_e32 v82, v14, v82
	v_add_f32_e32 v82, v15, v82
	v_add_f32_e32 v82, v83, v82
.Ljoin666:
	v_cvt_pk_bf16_f32 v2, v81, v2
	v_cvt_pk_bf16_f32 v3, v3, v4
	v_cvt_pk_bf16_f32 v4, v5, v6
	v_cvt_pk_bf16_f32 v5, v7, v8
	v_cvt_pk_bf16_f32 v6, v9, v10
	v_cvt_pk_bf16_f32 v7, v11, v12
	v_cvt_pk_bf16_f32 v8, v13, v14
	v_cvt_pk_bf16_f32 v9, v15, v83
	ds_read_b128 v[212:215], v0 offset:34880
	ds_read_b128 v[216:219], v0 offset:34912
	ds_read_b128 v[220:223], v0 offset:39488
	ds_read_b128 v[224:227], v0 offset:39520
	ds_read_b128 v[228:231], v0 offset:44096
	ds_read_b128 v[236:239], v0 offset:44128
	ds_read_b128 v[240:243], v0 offset:48704
	ds_read_b128 v[244:247], v0 offset:48736
	v_add_f32_e32 v173, v80, v82
	s_waitcnt lgkmcnt(7)
	v_mfma_f32_32x32x16_bf16 v[64:79], v[212:215], v[2:5], v[64:79]
	s_waitcnt lgkmcnt(6)
	v_mfma_f32_32x32x16_bf16 v[64:79], v[216:219], v[6:9], v[64:79]
	s_waitcnt lgkmcnt(5)
	v_mfma_f32_32x32x16_bf16 v[48:63], v[220:223], v[2:5], v[48:63]
	s_waitcnt lgkmcnt(4)
	v_mfma_f32_32x32x16_bf16 v[48:63], v[224:227], v[6:9], v[48:63]
	s_waitcnt lgkmcnt(3)
	v_mfma_f32_32x32x16_bf16 v[32:47], v[228:231], v[2:5], v[32:47]
	s_waitcnt lgkmcnt(2)
	v_mfma_f32_32x32x16_bf16 v[32:47], v[236:239], v[6:9], v[32:47]
	s_waitcnt lgkmcnt(1)
	v_mfma_f32_32x32x16_bf16 v[16:31], v[240:243], v[2:5], v[16:31]
	s_waitcnt lgkmcnt(0)
	v_mfma_f32_32x32x16_bf16 v[16:31], v[244:247], v[6:9], v[16:31]

.LBB0_682:
	s_and_b32 s27, s8, 1
	s_sub_i32 s20, s54, 63
	s_cmp_gt_i32 s20, s51
	s_cbranch_scc1 .LBB0_688
	s_cmp_le_i32 s54, s33
	s_mul_i32 s2, s27, 0x4400
	s_cselect_b64 s[8:9], -1, 0
	s_lshl_b32 s3, s27, 8
	v_add_u32_e32 v181, s2, v156
	v_add_u32_e32 v185, s3, v153
	ds_read_b128 v[66:69], v185
	ds_read_b128 v[70:73], v185 offset:16
	ds_read_b128 v[74:77], v185 offset:64
	ds_read_b128 v[78:81], v185 offset:80
	ds_read_b128 v[212:215], v181
	ds_read_b128 v[216:219], v181 offset:32
	ds_read_b128 v[220:223], v181 offset:64
	ds_read_b128 v[224:227], v181 offset:96
	ds_read_b128 v[228:231], v181 offset:128
	ds_read_b128 v[236:239], v181 offset:160
	ds_read_b128 v[240:243], v181 offset:192
	ds_read_b128 v[244:247], v181 offset:224
	v_add_u32_e32 v183, s54, v132
	v_subrev_u32_e32 v180, 63, v183
	s_waitcnt lgkmcnt(7)
	v_mfma_f32_32x32x16_bf16 v[66:81], v[212:215], v[82:85], v[66:81]
	s_waitcnt lgkmcnt(6)
	v_mfma_f32_32x32x16_bf16 v[66:81], v[216:219], v[86:89], v[66:81]
	s_waitcnt lgkmcnt(5)
	v_mfma_f32_32x32x16_bf16 v[66:81], v[220:223], v[90:93], v[66:81]
	s_waitcnt lgkmcnt(4)
	v_mfma_f32_32x32x16_bf16 v[66:81], v[224:227], v[94:97], v[66:81]
	s_waitcnt lgkmcnt(3)
	v_mfma_f32_32x32x16_bf16 v[66:81], v[228:231], v[98:101], v[66:81]
	s_waitcnt lgkmcnt(2)
	v_mfma_f32_32x32x16_bf16 v[66:81], v[236:239], v[102:105], v[66:81]
	s_waitcnt lgkmcnt(1)
	v_mfma_f32_32x32x16_bf16 v[66:81], v[240:243], v[106:109], v[66:81]
	s_waitcnt lgkmcnt(0)
	v_mfma_f32_32x32x16_bf16 v[66:81], v[244:247], v[110:113], v[66:81]
	v_cmp_le_i32_e32 vcc, v180, v0
	s_nop 10
	v_add_f32_e32 v66, 0, v66
	s_or_b64 vcc, s[8:9], vcc
	v_cndmask_b32_e32 v192, v162, v66, vcc
	v_cmp_lt_i32_e32 vcc, v180, v0
	v_add_f32_e32 v66, 0, v67
	s_or_b64 vcc, s[8:9], vcc
	v_subrev_u32_e32 v67, 61, v183
	v_cndmask_b32_e32 v191, v162, v66, vcc
	v_cmp_le_i32_e32 vcc, v67, v0
	v_add_f32_e32 v67, 0, v68
	s_or_b64 vcc, s[8:9], vcc
	v_cndmask_b32_e32 v190, v162, v67, vcc
	v_subrev_u32_e32 v67, 60, v183
	v_cmp_le_i32_e32 vcc, v67, v0
	v_add_f32_e32 v67, 0, v69
	s_or_b64 vcc, s[8:9], vcc
	v_cndmask_b32_e32 v189, v162, v67, vcc
	v_subrev_u32_e32 v67, 59, v183
	v_cmp_le_i32_e32 vcc, v67, v0
	v_add_f32_e32 v67, 0, v70
	s_or_b64 vcc, s[8:9], vcc
	v_cndmask_b32_e32 v188, v162, v67, vcc
	v_subrev_u32_e32 v67, 58, v183
	v_cmp_le_i32_e32 vcc, v67, v0
	v_add_f32_e32 v67, 0, v71
	s_or_b64 vcc, s[8:9], vcc
	v_cndmask_b32_e32 v187, v162, v67, vcc
	v_subrev_u32_e32 v67, 57, v183
	v_cmp_le_i32_e32 vcc, v67, v0
	v_add_f32_e32 v67, 0, v72
	s_or_b64 vcc, s[8:9], vcc
	v_cndmask_b32_e32 v186, v162, v67, vcc
	v_subrev_u32_e32 v67, 56, v183
	v_cmp_le_i32_e32 vcc, v67, v0
	v_add_f32_e32 v67, 0, v73
	s_or_b64 vcc, s[8:9], vcc
	v_cndmask_b32_e32 v184, v162, v67, vcc
	v_cmp_le_i32_e32 vcc, v180, v157
	v_add_f32_e32 v67, 0, v74
	s_or_b64 vcc, s[8:9], vcc
	v_cndmask_b32_e32 v73, v162, v67, vcc
	v_cmp_le_i32_e32 vcc, v180, v158
	v_add_f32_e32 v67, 0, v75
	s_or_b64 vcc, s[8:9], vcc
	v_cndmask_b32_e32 v72, v162, v67, vcc
	v_cmp_le_i32_e32 vcc, v180, v159
	v_add_f32_e32 v67, 0, v76
	s_or_b64 vcc, s[8:9], vcc
	v_cndmask_b32_e32 v71, v162, v67, vcc
	v_cmp_le_i32_e32 vcc, v180, v165
	v_max3_f32 v66, v192, s47, v191
	v_add_f32_e32 v67, 0, v77
	s_or_b64 vcc, s[8:9], vcc
	v_max3_f32 v66, v66, v190, v189
	v_cndmask_b32_e32 v70, v162, v67, vcc
	v_cmp_le_i32_e32 vcc, v180, v166
	v_max3_f32 v66, v66, v188, v187
	v_add_f32_e32 v67, 0, v78
	s_or_b64 vcc, s[8:9], vcc
	v_max3_f32 v66, v66, v186, v184
	v_cndmask_b32_e32 v69, v162, v67, vcc
	v_cmp_le_i32_e32 vcc, v180, v167
	v_max3_f32 v66, v66, v73, v72
	v_add_f32_e32 v67, 0, v79
	s_or_b64 vcc, s[8:9], vcc
	v_max3_f32 v66, v66, v71, v70
	v_cndmask_b32_e32 v68, v162, v67, vcc
	v_cmp_le_i32_e32 vcc, v180, v168
	v_max3_f32 v74, v66, v69, v68
	v_add_f32_e32 v66, 0, v80
	s_or_b64 vcc, s[8:9], vcc
	v_cndmask_b32_e32 v67, v162, v66, vcc
	v_cmp_le_i32_e32 vcc, v180, v169
	v_add_f32_e32 v66, 0, v81
	s_or_b64 vcc, s[8:9], vcc
	v_cndmask_b32_e32 v66, v162, v66, vcc
	v_max3_f32 v74, v74, v67, v66
	v_mov_b32_e32 v75, v74
	s_nop 1
	v_permlane32_swap_b32_e32 v74, v75
	v_max_f32_e32 v75, v75, v75
	v_max_f32_e32 v74, v74, v74
	v_max_f32_e32 v74, v74, v75
	v_cmp_gt_f32_e32 vcc, v74, v178
	s_cbranch_vccz .LBB0_685
	v_max_f32_e32 v74, v74, v74
	v_max_f32_e32 v75, v178, v178
	v_max_f32_e32 v75, v75, v74
	v_sub_f32_e32 v74, v178, v75
	v_exp_f32_e32 v74, v74
	v_mov_b32_e32 v178, v75
	v_pk_mul_f32 v[64:65], v[64:65], v[74:75] op_sel_hi:[1,0]
	v_pk_mul_f32 v[62:63], v[62:63], v[74:75] op_sel_hi:[1,0]
	v_pk_mul_f32 v[60:61], v[60:61], v[74:75] op_sel_hi:[1,0]
	v_pk_mul_f32 v[58:59], v[58:59], v[74:75] op_sel_hi:[1,0]
	v_pk_mul_f32 v[56:57], v[56:57], v[74:75] op_sel_hi:[1,0]
	v_pk_mul_f32 v[54:55], v[54:55], v[74:75] op_sel_hi:[1,0]
	v_pk_mul_f32 v[52:53], v[52:53], v[74:75] op_sel_hi:[1,0]
	v_pk_mul_f32 v[50:51], v[50:51], v[74:75] op_sel_hi:[1,0]
	v_pk_mul_f32 v[48:49], v[48:49], v[74:75] op_sel_hi:[1,0]
	v_pk_mul_f32 v[46:47], v[46:47], v[74:75] op_sel_hi:[1,0]
	v_pk_mul_f32 v[44:45], v[44:45], v[74:75] op_sel_hi:[1,0]
	v_pk_mul_f32 v[42:43], v[42:43], v[74:75] op_sel_hi:[1,0]
	v_pk_mul_f32 v[40:41], v[40:41], v[74:75] op_sel_hi:[1,0]
	v_pk_mul_f32 v[38:39], v[38:39], v[74:75] op_sel_hi:[1,0]
	v_pk_mul_f32 v[36:37], v[36:37], v[74:75] op_sel_hi:[1,0]
	v_pk_mul_f32 v[34:35], v[34:35], v[74:75] op_sel_hi:[1,0]
	v_pk_mul_f32 v[32:33], v[32:33], v[74:75] op_sel_hi:[1,0]
	v_pk_mul_f32 v[30:31], v[30:31], v[74:75] op_sel_hi:[1,0]
	v_pk_mul_f32 v[28:29], v[28:29], v[74:75] op_sel_hi:[1,0]
	v_pk_mul_f32 v[26:27], v[26:27], v[74:75] op_sel_hi:[1,0]
	v_pk_mul_f32 v[24:25], v[24:25], v[74:75] op_sel_hi:[1,0]
	v_pk_mul_f32 v[22:23], v[22:23], v[74:75] op_sel_hi:[1,0]
	v_pk_mul_f32 v[20:21], v[20:21], v[74:75] op_sel_hi:[1,0]
	v_pk_mul_f32 v[18:19], v[18:19], v[74:75] op_sel_hi:[1,0]
	v_pk_mul_f32 v[16:17], v[16:17], v[74:75] op_sel_hi:[1,0]
	v_pk_mul_f32 v[14:15], v[14:15], v[74:75] op_sel_hi:[1,0]
	v_pk_mul_f32 v[12:13], v[12:13], v[74:75] op_sel_hi:[1,0]
	v_pk_mul_f32 v[10:11], v[10:11], v[74:75] op_sel_hi:[1,0]
	v_pk_mul_f32 v[8:9], v[8:9], v[74:75] op_sel_hi:[1,0]
	v_pk_mul_f32 v[6:7], v[6:7], v[74:75] op_sel_hi:[1,0]
	v_pk_mul_f32 v[4:5], v[4:5], v[74:75] op_sel_hi:[1,0]
	v_pk_mul_f32 v[2:3], v[2:3], v[74:75] op_sel_hi:[1,0]
	v_mul_f32_e32 v179, v179, v74
.LBB0_685:
	s_cmp_lg_u32 s8, 0
	s_cbranch_scc1 .Llean685
	v_sub_f32_e32 v74, v192, v178
	v_exp_f32_e32 v74, v74
	v_sub_f32_e32 v75, v191, v178
	v_cmp_lt_f32_e32 vcc, s49, v192
	v_exp_f32_e32 v75, v75
	s_or_b64 vcc, s[8:9], vcc
	v_sub_f32_e32 v77, v190, v178
	v_cndmask_b32_e32 v74, 0, v74, vcc
	v_cmp_lt_f32_e32 vcc, s49, v191
	v_exp_f32_e32 v77, v77
	s_or_b64 vcc, s[8:9], vcc
	v_sub_f32_e32 v78, v189, v178
	v_cndmask_b32_e32 v75, 0, v75, vcc
	v_cmp_lt_f32_e32 vcc, s49, v190
	v_exp_f32_e32 v78, v78
	s_or_b64 vcc, s[8:9], vcc
	v_sub_f32_e32 v79, v188, v178
	v_cndmask_b32_e32 v77, 0, v77, vcc
	v_cmp_lt_f32_e32 vcc, s49, v189
	v_exp_f32_e32 v79, v79
	s_or_b64 vcc, s[8:9], vcc
	v_sub_f32_e32 v80, v187, v178
	v_cndmask_b32_e32 v78, 0, v78, vcc
	v_cmp_lt_f32_e32 vcc, s49, v188
	v_exp_f32_e32 v80, v80
	s_or_b64 vcc, s[8:9], vcc
	v_cndmask_b32_e32 v79, 0, v79, vcc
	v_cmp_lt_f32_e32 vcc, s49, v187
	v_sub_f32_e32 v81, v186, v178
	s_or_b64 vcc, s[8:9], vcc
	v_exp_f32_e32 v81, v81
	v_cndmask_b32_e32 v80, 0, v80, vcc
	v_cmp_lt_f32_e32 vcc, s49, v186
	v_sub_f32_e32 v186, v184, v178
	v_exp_f32_e32 v186, v186
	s_or_b64 vcc, s[8:9], vcc
	v_cndmask_b32_e32 v81, 0, v81, vcc
	v_cmp_lt_f32_e32 vcc, s49, v184
	s_or_b64 vcc, s[8:9], vcc
	v_add_f32_e32 v76, 0, v74
	v_cndmask_b32_e32 v184, 0, v186, vcc
	v_sub_f32_e32 v186, v73, v178
	v_exp_f32_e32 v186, v186
	v_cmp_lt_f32_e32 vcc, s49, v73
	s_or_b64 vcc, s[8:9], vcc
	v_add_f32_e32 v76, v75, v76
	v_cndmask_b32_e32 v73, 0, v186, vcc
	v_sub_f32_e32 v186, v72, v178
	v_exp_f32_e32 v186, v186
	v_cmp_lt_f32_e32 vcc, s49, v72
	s_or_b64 vcc, s[8:9], vcc
	v_add_f32_e32 v76, v77, v76
	v_cndmask_b32_e32 v72, 0, v186, vcc
	v_sub_f32_e32 v186, v71, v178
	v_exp_f32_e32 v186, v186
	v_cmp_lt_f32_e32 vcc, s49, v71
	s_or_b64 vcc, s[8:9], vcc
	v_add_f32_e32 v76, v78, v76
	v_cndmask_b32_e32 v71, 0, v186, vcc
	v_sub_f32_e32 v186, v70, v178
	v_exp_f32_e32 v186, v186
	v_add_f32_e32 v76, v79, v76
	v_add_f32_e32 v76, v80, v76
	v_cmp_lt_f32_e32 vcc, s49, v70
	v_sub_f32_e32 v70, v69, v178
	v_add_f32_e32 v76, v81, v76
	s_or_b64 vcc, s[8:9], vcc
	v_exp_f32_e32 v70, v70
	v_add_f32_e32 v76, v184, v76
	v_cndmask_b32_e32 v186, 0, v186, vcc
	v_cmp_lt_f32_e32 vcc, s49, v69
	v_sub_f32_e32 v69, v68, v178
	v_add_f32_e32 v76, v73, v76
	v_exp_f32_e32 v69, v69
	v_add_f32_e32 v76, v72, v76
	s_or_b64 vcc, s[8:9], vcc
	v_add_f32_e32 v76, v71, v76
	v_cndmask_b32_e32 v187, 0, v70, vcc
	v_cmp_lt_f32_e32 vcc, s49, v68
	v_sub_f32_e32 v68, v67, v178
	v_add_f32_e32 v76, v186, v76
	s_or_b64 vcc, s[8:9], vcc
	v_exp_f32_e32 v68, v68
	v_add_f32_e32 v70, v187, v76
	v_cndmask_b32_e32 v76, 0, v69, vcc
	v_cmp_lt_f32_e32 vcc, s49, v67
	v_sub_f32_e32 v67, v66, v178
	v_exp_f32_e32 v67, v67
	s_or_b64 vcc, s[8:9], vcc
	v_cndmask_b32_e32 v188, 0, v68, vcc
	v_cmp_lt_f32_e32 vcc, s49, v66
	v_add_f32_e32 v69, v76, v70
	s_or_b64 vcc, s[8:9], vcc
	v_add_f32_e32 v68, v188, v69
	v_cndmask_b32_e32 v189, 0, v67, vcc
	v_add_f32_e32 v190, v189, v68
	s_branch .Ljoin685
.Llean685:
	v_sub_f32_e32 v74, v192, v178
	v_exp_f32_e32 v74, v74
	v_sub_f32_e32 v75, v191, v178
	v_exp_f32_e32 v75, v75
	v_sub_f32_e32 v77, v190, v178
	v_exp_f32_e32 v77, v77
	v_sub_f32_e32 v78, v189, v178
	v_exp_f32_e32 v78, v78
	v_sub_f32_e32 v79, v188, v178
	v_exp_f32_e32 v79, v79
	v_sub_f32_e32 v80, v187, v178
	v_exp_f32_e32 v80, v80
	v_sub_f32_e32 v81, v186, v178
	v_exp_f32_e32 v81, v81
	v_sub_f32_e32 v186, v184, v178
	v_exp_f32_e32 v186, v186
	v_add_f32_e32 v76, 0, v74
	v_mov_b32_e32 v184, v186
	v_sub_f32_e32 v186, v73, v178
	v_exp_f32_e32 v186, v186
	v_add_f32_e32 v76, v75, v76
	v_mov_b32_e32 v73, v186
	v_sub_f32_e32 v186, v72, v178
	v_exp_f32_e32 v186, v186
	v_add_f32_e32 v76, v77, v76
	v_mov_b32_e32 v72, v186
	v_sub_f32_e32 v186, v71, v178
	v_exp_f32_e32 v186, v186
	v_add_f32_e32 v76, v78, v76
	v_mov_b32_e32 v71, v186
	v_sub_f32_e32 v186, v70, v178
	v_exp_f32_e32 v186, v186
	v_add_f32_e32 v76, v79, v76
	v_add_f32_e32 v76, v80, v76
	v_sub_f32_e32 v70, v69, v178
	v_add_f32_e32 v76, v81, v76
	v_exp_f32_e32 v70, v70
	v_add_f32_e32 v76, v184, v76
	v_sub_f32_e32 v69, v68, v178
	v_add_f32_e32 v76, v73, v76
	v_exp_f32_e32 v69, v69
	v_add_f32_e32 v76, v72, v76
	v_add_f32_e32 v76, v71, v76
	v_mov_b32_e32 v187, v70
	v_sub_f32_e32 v68, v67, v178
	v_add_f32_e32 v76, v186, v76
	v_exp_f32_e32 v68, v68
	v_add_f32_e32 v70, v187, v76
	v_mov_b32_e32 v76, v69
	v_sub_f32_e32 v67, v66, v178
	v_exp_f32_e32 v67, v67
	v_mov_b32_e32 v188, v68
	v_add_f32_e32 v69, v76, v70
	v_add_f32_e32 v68, v188, v69
	v_mov_b32_e32 v189, v67
	v_add_f32_e32 v190, v189, v68
.Ljoin685:
	v_cvt_pk_bf16_f32 v66, v74, v75
	v_cvt_pk_bf16_f32 v67, v77, v78
	v_cvt_pk_bf16_f32 v68, v79, v80
	v_cvt_pk_bf16_f32 v69, v81, v184
	v_cvt_pk_bf16_f32 v70, v73, v72
	v_cvt_pk_bf16_f32 v71, v71, v186
	v_cvt_pk_bf16_f32 v72, v187, v76
	v_cvt_pk_bf16_f32 v73, v188, v189
	s_mul_i32 s2, s27, 0x4800
	v_add_u32_e32 v184, s2, v155
	ds_read_b128 v[212:215], v184 offset:34816
	ds_read_b128 v[216:219], v184 offset:34848
	ds_read_b128 v[220:223], v184 offset:39424
	ds_read_b128 v[224:227], v184 offset:39456
	ds_read_b128 v[228:231], v184 offset:44032
	ds_read_b128 v[236:239], v184 offset:44064
	ds_read_b128 v[240:243], v184 offset:48640
	ds_read_b128 v[244:247], v184 offset:48672
	v_add_f32_e32 v179, v179, v190
	s_waitcnt lgkmcnt(7)
	v_mfma_f32_32x32x16_bf16 v[50:65], v[212:215], v[66:69], v[50:65]
	s_waitcnt lgkmcnt(6)
	v_mfma_f32_32x32x16_bf16 v[50:65], v[216:219], v[70:73], v[50:65]
	s_waitcnt lgkmcnt(5)
	v_mfma_f32_32x32x16_bf16 v[34:49], v[220:223], v[66:69], v[34:49]
	s_waitcnt lgkmcnt(4)
	v_mfma_f32_32x32x16_bf16 v[34:49], v[224:227], v[70:73], v[34:49]
	s_waitcnt lgkmcnt(3)
	v_mfma_f32_32x32x16_bf16 v[18:33], v[228:231], v[66:69], v[18:33]
	s_waitcnt lgkmcnt(2)
	v_mfma_f32_32x32x16_bf16 v[18:33], v[236:239], v[70:73], v[18:33]
	s_waitcnt lgkmcnt(1)
	v_mfma_f32_32x32x16_bf16 v[2:17], v[240:243], v[66:69], v[2:17]
	s_waitcnt lgkmcnt(0)
	v_mfma_f32_32x32x16_bf16 v[2:17], v[244:247], v[70:73], v[2:17]
	ds_read_b128 v[66:69], v185 offset:128
	ds_read_b128 v[70:73], v185 offset:144
	ds_read_b128 v[74:77], v185 offset:192
	ds_read_b128 v[78:81], v185 offset:208
	ds_read_b128 v[212:215], v181 offset:8704
	ds_read_b128 v[216:219], v181 offset:8736
	ds_read_b128 v[220:223], v181 offset:8768
	ds_read_b128 v[224:227], v181 offset:8800
	ds_read_b128 v[228:231], v181 offset:8832
	ds_read_b128 v[236:239], v181 offset:8864
	ds_read_b128 v[240:243], v181 offset:8896
	ds_read_b128 v[244:247], v181 offset:8928
	s_waitcnt lgkmcnt(7)
	v_mfma_f32_32x32x16_bf16 v[66:81], v[212:215], v[82:85], v[66:81]
	s_waitcnt lgkmcnt(6)
	v_mfma_f32_32x32x16_bf16 v[66:81], v[216:219], v[86:89], v[66:81]
	s_waitcnt lgkmcnt(5)
	v_mfma_f32_32x32x16_bf16 v[66:81], v[220:223], v[90:93], v[66:81]
	s_waitcnt lgkmcnt(4)
	v_mfma_f32_32x32x16_bf16 v[66:81], v[224:227], v[94:97], v[66:81]
	s_waitcnt lgkmcnt(3)
	v_mfma_f32_32x32x16_bf16 v[66:81], v[228:231], v[98:101], v[66:81]
	s_waitcnt lgkmcnt(2)
	v_mfma_f32_32x32x16_bf16 v[66:81], v[236:239], v[102:105], v[66:81]
	s_waitcnt lgkmcnt(1)
	v_mfma_f32_32x32x16_bf16 v[66:81], v[240:243], v[106:109], v[66:81]
	s_waitcnt lgkmcnt(0)
	v_mfma_f32_32x32x16_bf16 v[66:81], v[244:247], v[110:113], v[66:81]
	v_subrev_u32_e32 v181, 31, v183
	v_cmp_le_i32_e32 vcc, v181, v0
	s_nop 9
	v_add_f32_e32 v66, 0, v66
	s_or_b64 vcc, s[8:9], vcc
	v_cndmask_b32_e32 v191, v162, v66, vcc
	v_cmp_lt_i32_e32 vcc, v181, v0
	v_add_f32_e32 v66, 0, v67
	s_or_b64 vcc, s[8:9], vcc
	v_subrev_u32_e32 v67, 29, v183
	v_cndmask_b32_e32 v190, v162, v66, vcc
	v_cmp_le_i32_e32 vcc, v67, v0
	v_add_f32_e32 v67, 0, v68
	s_or_b64 vcc, s[8:9], vcc
	v_cndmask_b32_e32 v189, v162, v67, vcc
	v_subrev_u32_e32 v67, 28, v183
	v_cmp_le_i32_e32 vcc, v67, v0
	v_add_f32_e32 v67, 0, v69
	s_or_b64 vcc, s[8:9], vcc
	v_cndmask_b32_e32 v188, v162, v67, vcc
	v_subrev_u32_e32 v67, 27, v183
	v_cmp_le_i32_e32 vcc, v67, v0
	v_add_f32_e32 v67, 0, v70
	s_or_b64 vcc, s[8:9], vcc
	v_cndmask_b32_e32 v187, v162, v67, vcc
	v_subrev_u32_e32 v67, 26, v183
	v_cmp_le_i32_e32 vcc, v67, v0
	v_add_f32_e32 v67, 0, v71
	s_or_b64 vcc, s[8:9], vcc
	v_cndmask_b32_e32 v186, v162, v67, vcc
	v_subrev_u32_e32 v67, 25, v183
	v_cmp_le_i32_e32 vcc, v67, v0
	v_add_f32_e32 v67, 0, v72
	s_or_b64 vcc, s[8:9], vcc
	v_cndmask_b32_e32 v185, v162, v67, vcc
	v_subrev_u32_e32 v67, 24, v183
	v_cmp_le_i32_e32 vcc, v67, v0
	v_add_f32_e32 v67, 0, v73
	s_or_b64 vcc, s[8:9], vcc
	v_cndmask_b32_e32 v181, v162, v67, vcc
	v_cmp_le_i32_e32 vcc, v180, v170
	v_add_f32_e32 v67, 0, v74
	s_or_b64 vcc, s[8:9], vcc
	v_cndmask_b32_e32 v73, v162, v67, vcc
	v_cmp_le_i32_e32 vcc, v180, v171
	v_add_f32_e32 v67, 0, v75
	s_or_b64 vcc, s[8:9], vcc
	v_cndmask_b32_e32 v72, v162, v67, vcc
	v_cmp_le_i32_e32 vcc, v180, v172
	v_add_f32_e32 v67, 0, v76
	s_or_b64 vcc, s[8:9], vcc
	v_cndmask_b32_e32 v71, v162, v67, vcc
	v_cmp_le_i32_e32 vcc, v180, v173
	v_max3_f32 v66, v191, s47, v190
	v_add_f32_e32 v67, 0, v77
	s_or_b64 vcc, s[8:9], vcc
	v_max3_f32 v66, v66, v189, v188
	v_cndmask_b32_e32 v70, v162, v67, vcc
	v_cmp_le_i32_e32 vcc, v180, v174
	v_max3_f32 v66, v66, v187, v186
	v_add_f32_e32 v67, 0, v78
	s_or_b64 vcc, s[8:9], vcc
	v_max3_f32 v66, v66, v185, v181
	v_cndmask_b32_e32 v69, v162, v67, vcc
	v_cmp_le_i32_e32 vcc, v180, v175
	v_max3_f32 v66, v66, v73, v72
	v_add_f32_e32 v67, 0, v79
	s_or_b64 vcc, s[8:9], vcc
	v_max3_f32 v66, v66, v71, v70
	v_cndmask_b32_e32 v68, v162, v67, vcc
	v_cmp_le_i32_e32 vcc, v180, v176
	v_max3_f32 v74, v66, v69, v68
	v_add_f32_e32 v66, 0, v80
	s_or_b64 vcc, s[8:9], vcc
	v_cndmask_b32_e32 v67, v162, v66, vcc
	v_cmp_le_i32_e32 vcc, v180, v177
	v_add_f32_e32 v66, 0, v81
	s_or_b64 vcc, s[8:9], vcc
	v_cndmask_b32_e32 v66, v162, v66, vcc
	v_max3_f32 v74, v74, v67, v66
	v_mov_b32_e32 v75, v74
	s_nop 1
	v_permlane32_swap_b32_e32 v74, v75
	v_max_f32_e32 v75, v75, v75
	v_max_f32_e32 v74, v74, v74
	v_max_f32_e32 v74, v74, v75
	v_cmp_gt_f32_e32 vcc, v74, v178
	s_cbranch_vccz .LBB0_687
	v_max_f32_e32 v74, v74, v74
	v_max_f32_e32 v75, v178, v178
	v_max_f32_e32 v75, v75, v74
	v_sub_f32_e32 v74, v178, v75
	v_exp_f32_e32 v74, v74
	v_mov_b32_e32 v178, v75
	v_pk_mul_f32 v[64:65], v[64:65], v[74:75] op_sel_hi:[1,0]
	v_pk_mul_f32 v[62:63], v[62:63], v[74:75] op_sel_hi:[1,0]
	v_pk_mul_f32 v[60:61], v[60:61], v[74:75] op_sel_hi:[1,0]
	v_pk_mul_f32 v[58:59], v[58:59], v[74:75] op_sel_hi:[1,0]
	v_pk_mul_f32 v[56:57], v[56:57], v[74:75] op_sel_hi:[1,0]
	v_pk_mul_f32 v[54:55], v[54:55], v[74:75] op_sel_hi:[1,0]
	v_pk_mul_f32 v[52:53], v[52:53], v[74:75] op_sel_hi:[1,0]
	v_pk_mul_f32 v[50:51], v[50:51], v[74:75] op_sel_hi:[1,0]
	v_pk_mul_f32 v[48:49], v[48:49], v[74:75] op_sel_hi:[1,0]
	v_pk_mul_f32 v[46:47], v[46:47], v[74:75] op_sel_hi:[1,0]
	v_pk_mul_f32 v[44:45], v[44:45], v[74:75] op_sel_hi:[1,0]
	v_pk_mul_f32 v[42:43], v[42:43], v[74:75] op_sel_hi:[1,0]
	v_pk_mul_f32 v[40:41], v[40:41], v[74:75] op_sel_hi:[1,0]
	v_pk_mul_f32 v[38:39], v[38:39], v[74:75] op_sel_hi:[1,0]
	v_pk_mul_f32 v[36:37], v[36:37], v[74:75] op_sel_hi:[1,0]
	v_pk_mul_f32 v[34:35], v[34:35], v[74:75] op_sel_hi:[1,0]
	v_pk_mul_f32 v[32:33], v[32:33], v[74:75] op_sel_hi:[1,0]
	v_pk_mul_f32 v[30:31], v[30:31], v[74:75] op_sel_hi:[1,0]
	v_pk_mul_f32 v[28:29], v[28:29], v[74:75] op_sel_hi:[1,0]
	v_pk_mul_f32 v[26:27], v[26:27], v[74:75] op_sel_hi:[1,0]
	v_pk_mul_f32 v[24:25], v[24:25], v[74:75] op_sel_hi:[1,0]
	v_pk_mul_f32 v[22:23], v[22:23], v[74:75] op_sel_hi:[1,0]
	v_pk_mul_f32 v[20:21], v[20:21], v[74:75] op_sel_hi:[1,0]
	v_pk_mul_f32 v[18:19], v[18:19], v[74:75] op_sel_hi:[1,0]
	v_pk_mul_f32 v[16:17], v[16:17], v[74:75] op_sel_hi:[1,0]
	v_pk_mul_f32 v[14:15], v[14:15], v[74:75] op_sel_hi:[1,0]
	v_pk_mul_f32 v[12:13], v[12:13], v[74:75] op_sel_hi:[1,0]
	v_pk_mul_f32 v[10:11], v[10:11], v[74:75] op_sel_hi:[1,0]
	v_pk_mul_f32 v[8:9], v[8:9], v[74:75] op_sel_hi:[1,0]
	v_pk_mul_f32 v[6:7], v[6:7], v[74:75] op_sel_hi:[1,0]
	v_pk_mul_f32 v[4:5], v[4:5], v[74:75] op_sel_hi:[1,0]
	v_pk_mul_f32 v[2:3], v[2:3], v[74:75] op_sel_hi:[1,0]
	v_mul_f32_e32 v179, v179, v74
.LBB0_687:
	s_cmp_lg_u32 s8, 0
	s_cbranch_scc1 .Llean687
	v_sub_f32_e32 v74, v191, v178
	v_exp_f32_e32 v74, v74
	v_sub_f32_e32 v75, v190, v178
	v_cmp_lt_f32_e32 vcc, s49, v191
	v_exp_f32_e32 v75, v75
	s_or_b64 vcc, s[8:9], vcc
	v_sub_f32_e32 v77, v189, v178
	v_cndmask_b32_e32 v74, 0, v74, vcc
	v_cmp_lt_f32_e32 vcc, s49, v190
	v_exp_f32_e32 v77, v77
	s_or_b64 vcc, s[8:9], vcc
	v_sub_f32_e32 v78, v188, v178
	v_cndmask_b32_e32 v75, 0, v75, vcc
	v_cmp_lt_f32_e32 vcc, s49, v189
	v_exp_f32_e32 v78, v78
	s_or_b64 vcc, s[8:9], vcc
	v_sub_f32_e32 v79, v187, v178
	v_cndmask_b32_e32 v77, 0, v77, vcc
	v_cmp_lt_f32_e32 vcc, s49, v188
	v_exp_f32_e32 v79, v79
	s_or_b64 vcc, s[8:9], vcc
	v_sub_f32_e32 v80, v186, v178
	v_cndmask_b32_e32 v78, 0, v78, vcc
	v_cmp_lt_f32_e32 vcc, s49, v187
	v_exp_f32_e32 v80, v80
	s_or_b64 vcc, s[8:9], vcc
	v_sub_f32_e32 v81, v185, v178
	v_cndmask_b32_e32 v79, 0, v79, vcc
	v_cmp_lt_f32_e32 vcc, s49, v186
	v_exp_f32_e32 v81, v81
	s_or_b64 vcc, s[8:9], vcc
	v_cndmask_b32_e32 v80, 0, v80, vcc
	v_cmp_lt_f32_e32 vcc, s49, v185
	v_sub_f32_e32 v180, v181, v178
	s_or_b64 vcc, s[8:9], vcc
	v_exp_f32_e32 v180, v180
	v_cndmask_b32_e32 v81, 0, v81, vcc
	v_cmp_lt_f32_e32 vcc, s49, v181
	v_sub_f32_e32 v181, v73, v178
	v_exp_f32_e32 v181, v181
	s_or_b64 vcc, s[8:9], vcc
	v_cndmask_b32_e32 v180, 0, v180, vcc
	v_cmp_lt_f32_e32 vcc, s49, v73
	s_or_b64 vcc, s[8:9], vcc
	v_add_f32_e32 v76, 0, v74
	v_cndmask_b32_e32 v73, 0, v181, vcc
	v_sub_f32_e32 v181, v72, v178
	v_exp_f32_e32 v181, v181
	v_cmp_lt_f32_e32 vcc, s49, v72
	s_or_b64 vcc, s[8:9], vcc
	v_add_f32_e32 v76, v75, v76
	v_cndmask_b32_e32 v72, 0, v181, vcc
	v_sub_f32_e32 v181, v71, v178
	v_exp_f32_e32 v181, v181
	v_cmp_lt_f32_e32 vcc, s49, v71
	s_or_b64 vcc, s[8:9], vcc
	v_add_f32_e32 v76, v77, v76
	v_cndmask_b32_e32 v71, 0, v181, vcc
	v_sub_f32_e32 v181, v70, v178
	v_add_f32_e32 v76, v78, v76
	v_exp_f32_e32 v181, v181
	v_add_f32_e32 v76, v79, v76
	v_add_f32_e32 v76, v80, v76
	v_cmp_lt_f32_e32 vcc, s49, v70
	v_sub_f32_e32 v70, v69, v178
	v_add_f32_e32 v76, v81, v76
	s_or_b64 vcc, s[8:9], vcc
	v_exp_f32_e32 v70, v70
	v_add_f32_e32 v76, v180, v76
	v_cndmask_b32_e32 v181, 0, v181, vcc
	v_cmp_lt_f32_e32 vcc, s49, v69
	v_sub_f32_e32 v69, v68, v178
	v_add_f32_e32 v76, v73, v76
	v_exp_f32_e32 v69, v69
	v_add_f32_e32 v76, v72, v76
	s_or_b64 vcc, s[8:9], vcc
	v_add_f32_e32 v76, v71, v76
	v_cndmask_b32_e32 v183, 0, v70, vcc
	v_cmp_lt_f32_e32 vcc, s49, v68
	v_sub_f32_e32 v68, v67, v178
	v_add_f32_e32 v76, v181, v76
	s_or_b64 vcc, s[8:9], vcc
	v_exp_f32_e32 v68, v68
	v_add_f32_e32 v70, v183, v76
	v_cndmask_b32_e32 v76, 0, v69, vcc
	v_cmp_lt_f32_e32 vcc, s49, v67
	v_sub_f32_e32 v67, v66, v178
	v_exp_f32_e32 v67, v67
	s_or_b64 vcc, s[8:9], vcc
	v_cndmask_b32_e32 v185, 0, v68, vcc
	v_cmp_lt_f32_e32 vcc, s49, v66
	v_add_f32_e32 v69, v76, v70
	s_or_b64 vcc, s[8:9], vcc
	v_add_f32_e32 v68, v185, v69
	v_cndmask_b32_e32 v186, 0, v67, vcc
	v_add_f32_e32 v187, v186, v68
	s_branch .Ljoin687
.Llean687:
	v_sub_f32_e32 v74, v191, v178
	v_exp_f32_e32 v74, v74
	v_sub_f32_e32 v75, v190, v178
	v_exp_f32_e32 v75, v75
	v_sub_f32_e32 v77, v189, v178
	v_exp_f32_e32 v77, v77
	v_sub_f32_e32 v78, v188, v178
	v_exp_f32_e32 v78, v78
	v_sub_f32_e32 v79, v187, v178
	v_exp_f32_e32 v79, v79
	v_sub_f32_e32 v80, v186, v178
	v_exp_f32_e32 v80, v80
	v_sub_f32_e32 v81, v185, v178
	v_exp_f32_e32 v81, v81
	v_sub_f32_e32 v180, v181, v178
	v_exp_f32_e32 v180, v180
	v_sub_f32_e32 v181, v73, v178
	v_exp_f32_e32 v181, v181
	v_add_f32_e32 v76, 0, v74
	v_mov_b32_e32 v73, v181
	v_sub_f32_e32 v181, v72, v178
	v_exp_f32_e32 v181, v181
	v_add_f32_e32 v76, v75, v76
	v_mov_b32_e32 v72, v181
	v_sub_f32_e32 v181, v71, v178
	v_exp_f32_e32 v181, v181
	v_add_f32_e32 v76, v77, v76
	v_mov_b32_e32 v71, v181
	v_sub_f32_e32 v181, v70, v178
	v_add_f32_e32 v76, v78, v76
	v_exp_f32_e32 v181, v181
	v_add_f32_e32 v76, v79, v76
	v_add_f32_e32 v76, v80, v76
	v_sub_f32_e32 v70, v69, v178
	v_add_f32_e32 v76, v81, v76
	v_exp_f32_e32 v70, v70
	v_add_f32_e32 v76, v180, v76
	v_sub_f32_e32 v69, v68, v178
	v_add_f32_e32 v76, v73, v76
	v_exp_f32_e32 v69, v69
	v_add_f32_e32 v76, v72, v76
	v_add_f32_e32 v76, v71, v76
	v_mov_b32_e32 v183, v70
	v_sub_f32_e32 v68, v67, v178
	v_add_f32_e32 v76, v181, v76
	v_exp_f32_e32 v68, v68
	v_add_f32_e32 v70, v183, v76
	v_mov_b32_e32 v76, v69
	v_sub_f32_e32 v67, v66, v178
	v_exp_f32_e32 v67, v67
	v_mov_b32_e32 v185, v68
	v_add_f32_e32 v69, v76, v70
	v_add_f32_e32 v68, v185, v69
	v_mov_b32_e32 v186, v67
	v_add_f32_e32 v187, v186, v68
.Ljoin687:
	v_cvt_pk_bf16_f32 v66, v74, v75
	v_cvt_pk_bf16_f32 v67, v77, v78
	v_cvt_pk_bf16_f32 v68, v79, v80
	v_cvt_pk_bf16_f32 v69, v81, v180
	v_cvt_pk_bf16_f32 v70, v73, v72
	v_cvt_pk_bf16_f32 v71, v71, v181
	v_cvt_pk_bf16_f32 v72, v183, v76
	v_cvt_pk_bf16_f32 v73, v185, v186
	ds_read_b128 v[212:215], v184 offset:34880
	ds_read_b128 v[216:219], v184 offset:34912
	ds_read_b128 v[220:223], v184 offset:39488
	ds_read_b128 v[224:227], v184 offset:39520
	ds_read_b128 v[228:231], v184 offset:44096
	ds_read_b128 v[236:239], v184 offset:44128
	ds_read_b128 v[240:243], v184 offset:48704
	ds_read_b128 v[244:247], v184 offset:48736
	v_add_f32_e32 v179, v179, v187
	s_waitcnt lgkmcnt(7)
	v_mfma_f32_32x32x16_bf16 v[50:65], v[212:215], v[66:69], v[50:65]
	s_waitcnt lgkmcnt(6)
	v_mfma_f32_32x32x16_bf16 v[50:65], v[216:219], v[70:73], v[50:65]
	s_waitcnt lgkmcnt(5)
	v_mfma_f32_32x32x16_bf16 v[34:49], v[220:223], v[66:69], v[34:49]
	s_waitcnt lgkmcnt(4)
	v_mfma_f32_32x32x16_bf16 v[34:49], v[224:227], v[70:73], v[34:49]
	s_waitcnt lgkmcnt(3)
	v_mfma_f32_32x32x16_bf16 v[18:33], v[228:231], v[66:69], v[18:33]
	s_waitcnt lgkmcnt(2)
	v_mfma_f32_32x32x16_bf16 v[18:33], v[236:239], v[70:73], v[18:33]
	s_waitcnt lgkmcnt(1)
	v_mfma_f32_32x32x16_bf16 v[2:17], v[240:243], v[66:69], v[2:17]
	s_waitcnt lgkmcnt(0)
	v_mfma_f32_32x32x16_bf16 v[2:17], v[244:247], v[70:73], v[2:17]
